# in-proj epilogue: hand-written stage-wise silu/sigmoid path for sb_z/n_z/gate tiles (same per-element arithmetic, no dependent chains)
# speedup vs baseline: 1.0971x; 1.0096x over previous
; #define G_LDA(dst, ih, ks) _Pragma("unroll") for (int i = 0; i < 4; ++i) dst[i] = mk8(*(const u32x4*)(stage + ra + (((ih) * 4 + i) * 2 + (ks)) * 1024))
; #define G_LDB(dst, ks) _Pragma("unroll") for (int j = 0; j < 4; ++j) dst[j] = mk8(*(const u32x4*)(stage + TILE_B + rb + (j * 2 + (ks)) * 1024))
; #define G_MMA(ih, A, B) do { _Pragma("unroll") for (int i = 0; i < 4; ++i) _Pragma("unroll") for (int j = 0; j < 4; ++j) acc[(ih) * 4 + i][j] = MFMA16(A[i], B[j], acc[(ih) * 4 + i][j]); } while (0)
; DI void g_compute(const unsigned char* stage, int ra, int rb, f32x4 (&acc)[8][4]) {
;   bf16x8 b0[4], b1[4], a0[4], a1[4];
;   G_LDB(b0, 0); G_LDA(a0, 0, 0);
;   __builtin_amdgcn_sched_barrier(0);
;   G_LDA(a1, 1, 0);
;   G_MMA(0, a0, b0);
;   __builtin_amdgcn_sched_barrier(0);
;   G_LDB(b1, 1); G_LDA(a0, 0, 1);
;   G_MMA(1, a1, b0);
;   __builtin_amdgcn_sched_barrier(0);
;   G_LDA(a1, 1, 1);
;   G_MMA(0, a0, b1);
;   __builtin_amdgcn_sched_barrier(0);
;   G_MMA(1, a1, b1);
;   __builtin_amdgcn_sched_barrier(0);
; }
;     ...
;   for (int kt = 0; kt < KT; kt += 2) {
;     g_dma(base, off, (kt + 1) * kstep, buf1, w);
;     g_compute(buf0, ra, rb, acc);
;     asm volatile("s_waitcnt vmcnt(0)" ::: "memory");
;     __syncthreads();
;     const bool last = kt + 2 >= KT;
;     g_dma(last ? nbase : base, off, last ? 0 : (kt + 2) * kstep, buf0, w);
;     g_compute(buf1, ra, rb, acc);
;     asm volatile("s_waitcnt vmcnt(0)" ::: "memory");
;     __syncthreads();
.LgA_w1:
	s_barrier
	s_add_i32 m0, s44, 0x0
	v_mfma_f32_16x16x32_bf16 v[62:65], v[180:183], v[216:219], v[62:65]
	global_load_lds_dwordx4 v244, s[40:41]
	ds_read_b128 v[146:149], v199
	v_mfma_f32_16x16x32_bf16 v[54:57], v[180:183], v[220:223], v[54:57]
	ds_read_b128 v[150:153], v199 offset:2048
	s_add_i32 m0, s44, 0x400
	v_mfma_f32_16x16x32_bf16 v[46:49], v[180:183], v[224:227], v[46:49]
	global_load_lds_dwordx4 v245, s[40:41]
	ds_read_b128 v[154:157], v199 offset:4096
	v_mfma_f32_16x16x32_bf16 v[38:41], v[180:183], v[240:243], v[38:41]
	ds_read_b128 v[158:161], v199 offset:6144
	s_add_i32 m0, s44, 0x800
	v_mfma_f32_16x16x32_bf16 v[58:61], v[184:187], v[216:219], v[58:61]
	global_load_lds_dwordx4 v246, s[40:41]
	ds_read_b128 v[164:167], v197
	v_mfma_f32_16x16x32_bf16 v[50:53], v[184:187], v[220:223], v[50:53]
	ds_read_b128 v[168:171], v197 offset:2048
	s_add_i32 m0, s44, 0xc00
	v_mfma_f32_16x16x32_bf16 v[42:45], v[184:187], v[224:227], v[42:45]
	global_load_lds_dwordx4 v247, s[40:41]
	ds_read_b128 v[172:175], v197 offset:4096
	v_mfma_f32_16x16x32_bf16 v[34:37], v[184:187], v[240:243], v[34:37]
	ds_read_b128 v[176:179], v197 offset:6144
	s_add_i32 m0, s44, 0x1000
	v_mfma_f32_16x16x32_bf16 v[30:33], v[188:191], v[216:219], v[30:33]
	global_load_lds_dwordx4 v248, s[40:41]
	v_mfma_f32_16x16x32_bf16 v[22:25], v[188:191], v[220:223], v[22:25]
	s_add_i32 m0, s44, 0x1400
	v_mfma_f32_16x16x32_bf16 v[14:17], v[188:191], v[224:227], v[14:17]
	global_load_lds_dwordx4 v249, s[40:41]
	v_mfma_f32_16x16x32_bf16 v[10:13], v[188:191], v[240:243], v[10:13]
	s_add_i32 m0, s44, 0x1800
	v_mfma_f32_16x16x32_bf16 v[26:29], v[192:195], v[216:219], v[26:29]
	global_load_lds_dwordx4 v250, s[40:41]
	v_mfma_f32_16x16x32_bf16 v[18:21], v[192:195], v[220:223], v[18:21]
	s_add_i32 m0, s44, 0x1c00
	v_mfma_f32_16x16x32_bf16 v[6:9], v[192:195], v[224:227], v[6:9]
	global_load_lds_dwordx4 v251, s[40:41]
	v_mfma_f32_16x16x32_bf16 v[2:5], v[192:195], v[240:243], v[2:5]
	s_add_u32 s40, s40, 0x80
	s_addc_u32 s41, s41, 0
	s_waitcnt lgkmcnt(0)
	v_mfma_f32_16x16x32_bf16 v[126:129], v[164:167], v[146:149], v[126:129]
	v_mfma_f32_16x16x32_bf16 v[118:121], v[164:167], v[150:153], v[118:121]
	ds_read_b128 v[180:183], v197 offset:8192
	v_mfma_f32_16x16x32_bf16 v[110:113], v[164:167], v[154:157], v[110:113]
	v_mfma_f32_16x16x32_bf16 v[102:105], v[164:167], v[158:161], v[102:105]
	v_mfma_f32_16x16x32_bf16 v[122:125], v[168:171], v[146:149], v[122:125]
	ds_read_b128 v[184:187], v197 offset:10240
	v_mfma_f32_16x16x32_bf16 v[114:117], v[168:171], v[150:153], v[114:117]
	v_mfma_f32_16x16x32_bf16 v[106:109], v[168:171], v[154:157], v[106:109]
	v_mfma_f32_16x16x32_bf16 v[98:101], v[168:171], v[158:161], v[98:101]
	ds_read_b128 v[188:191], v197 offset:12288
	v_mfma_f32_16x16x32_bf16 v[94:97], v[172:175], v[146:149], v[94:97]
	v_mfma_f32_16x16x32_bf16 v[86:89], v[172:175], v[150:153], v[86:89]
	v_mfma_f32_16x16x32_bf16 v[78:81], v[172:175], v[154:157], v[78:81]
	ds_read_b128 v[192:195], v197 offset:14336
	v_mfma_f32_16x16x32_bf16 v[70:73], v[172:175], v[158:161], v[70:73]
	v_mfma_f32_16x16x32_bf16 v[90:93], v[176:179], v[146:149], v[90:93]
	v_mfma_f32_16x16x32_bf16 v[82:85], v[176:179], v[150:153], v[82:85]
	v_mfma_f32_16x16x32_bf16 v[74:77], v[176:179], v[154:157], v[74:77]
	v_mfma_f32_16x16x32_bf16 v[66:69], v[176:179], v[158:161], v[66:69]
	s_waitcnt lgkmcnt(0)
	v_mfma_f32_16x16x32_bf16 v[62:65], v[180:183], v[146:149], v[62:65]
	ds_read_b128 v[216:219], v199 offset:1024
	v_mfma_f32_16x16x32_bf16 v[54:57], v[180:183], v[150:153], v[54:57]
	v_mfma_f32_16x16x32_bf16 v[46:49], v[180:183], v[154:157], v[46:49]
	ds_read_b128 v[220:223], v199 offset:3072
	v_mfma_f32_16x16x32_bf16 v[38:41], v[180:183], v[158:161], v[38:41]
	v_mfma_f32_16x16x32_bf16 v[58:61], v[184:187], v[146:149], v[58:61]
	ds_read_b128 v[224:227], v199 offset:5120
	v_mfma_f32_16x16x32_bf16 v[50:53], v[184:187], v[150:153], v[50:53]
	v_mfma_f32_16x16x32_bf16 v[42:45], v[184:187], v[154:157], v[42:45]
	ds_read_b128 v[240:243], v199 offset:7168
	v_mfma_f32_16x16x32_bf16 v[34:37], v[184:187], v[158:161], v[34:37]
	v_mfma_f32_16x16x32_bf16 v[30:33], v[188:191], v[146:149], v[30:33]
	ds_read_b128 v[164:167], v197 offset:1024
	v_mfma_f32_16x16x32_bf16 v[22:25], v[188:191], v[150:153], v[22:25]
	ds_read_b128 v[168:171], v197 offset:3072
	v_mfma_f32_16x16x32_bf16 v[14:17], v[188:191], v[154:157], v[14:17]
	ds_read_b128 v[172:175], v197 offset:5120
	v_mfma_f32_16x16x32_bf16 v[10:13], v[188:191], v[158:161], v[10:13]
	ds_read_b128 v[176:179], v197 offset:7168
	v_mfma_f32_16x16x32_bf16 v[26:29], v[192:195], v[146:149], v[26:29]
	v_mfma_f32_16x16x32_bf16 v[18:21], v[192:195], v[150:153], v[18:21]
	v_mfma_f32_16x16x32_bf16 v[6:9], v[192:195], v[154:157], v[6:9]
	v_mfma_f32_16x16x32_bf16 v[2:5], v[192:195], v[158:161], v[2:5]
	s_waitcnt lgkmcnt(0)
	v_mfma_f32_16x16x32_bf16 v[126:129], v[164:167], v[216:219], v[126:129]
	v_mfma_f32_16x16x32_bf16 v[118:121], v[164:167], v[220:223], v[118:121]
	ds_read_b128 v[180:183], v197 offset:9216
	v_mfma_f32_16x16x32_bf16 v[110:113], v[164:167], v[224:227], v[110:113]
	v_mfma_f32_16x16x32_bf16 v[102:105], v[164:167], v[240:243], v[102:105]
	v_mfma_f32_16x16x32_bf16 v[122:125], v[168:171], v[216:219], v[122:125]
	ds_read_b128 v[184:187], v197 offset:11264
	v_mfma_f32_16x16x32_bf16 v[114:117], v[168:171], v[220:223], v[114:117]
	v_mfma_f32_16x16x32_bf16 v[106:109], v[168:171], v[224:227], v[106:109]
	v_mfma_f32_16x16x32_bf16 v[98:101], v[168:171], v[240:243], v[98:101]
	ds_read_b128 v[188:191], v197 offset:13312
	v_mfma_f32_16x16x32_bf16 v[94:97], v[172:175], v[216:219], v[94:97]
	v_mfma_f32_16x16x32_bf16 v[86:89], v[172:175], v[220:223], v[86:89]
	v_mfma_f32_16x16x32_bf16 v[78:81], v[172:175], v[224:227], v[78:81]
	ds_read_b128 v[192:195], v197 offset:15360
	v_mfma_f32_16x16x32_bf16 v[70:73], v[172:175], v[240:243], v[70:73]
	v_mfma_f32_16x16x32_bf16 v[90:93], v[176:179], v[216:219], v[90:93]
	v_mfma_f32_16x16x32_bf16 v[82:85], v[176:179], v[220:223], v[82:85]
	v_mfma_f32_16x16x32_bf16 v[74:77], v[176:179], v[224:227], v[74:77]
	v_mfma_f32_16x16x32_bf16 v[66:69], v[176:179], v[240:243], v[66:69]
	s_waitcnt lgkmcnt(0)
	s_waitcnt vmcnt(0)
	s_barrier
; #define G_LDA(dst, ih, ks) _Pragma("unroll") for (int i = 0; i < 4; ++i) dst[i] = mk8(*(const u32x4*)(stage + ra + (((ih) * 4 + i) * 2 + (ks)) * 1024))
; #define G_LDB(dst, ks) _Pragma("unroll") for (int j = 0; j < 4; ++j) dst[j] = mk8(*(const u32x4*)(stage + TILE_B + rb + (j * 2 + (ks)) * 1024))
; #define G_MMA(ih, A, B) do { _Pragma("unroll") for (int i = 0; i < 4; ++i) _Pragma("unroll") for (int j = 0; j < 4; ++j) acc[(ih) * 4 + i][j] = MFMA16(A[i], B[j], acc[(ih) * 4 + i][j]); } while (0)
; DI void g_compute(const unsigned char* stage, int ra, int rb, f32x4 (&acc)[8][4]) {
;   bf16x8 b0[4], b1[4], a0[4], a1[4];
;   G_LDB(b0, 0); G_LDA(a0, 0, 0);
;   __builtin_amdgcn_sched_barrier(0);
;   G_LDA(a1, 1, 0);
;   G_MMA(0, a0, b0);
;   __builtin_amdgcn_sched_barrier(0);
;   G_LDB(b1, 1); G_LDA(a0, 0, 1);
;   G_MMA(1, a1, b0);
;   __builtin_amdgcn_sched_barrier(0);
;   G_LDA(a1, 1, 1);
;   G_MMA(0, a0, b1);
;   __builtin_amdgcn_sched_barrier(0);
;   G_MMA(1, a1, b1);
;   __builtin_amdgcn_sched_barrier(0);
; }
;     ...
;   for (int kt = 0; kt < KT; kt += 2) {
;     g_dma(base, off, (kt + 1) * kstep, buf1, w);
;     g_compute(buf0, ra, rb, acc);
;     asm volatile("s_waitcnt vmcnt(0)" ::: "memory");
;     __syncthreads();
;     const bool last = kt + 2 >= KT;
;     g_dma(last ? nbase : base, off, last ? 0 : (kt + 2) * kstep, buf0, w);
;     g_compute(buf1, ra, rb, acc);
;     asm volatile("s_waitcnt vmcnt(0)" ::: "memory");
;     __syncthreads();
	s_add_i32 m0, s45, 0x0
	v_mfma_f32_16x16x32_bf16 v[62:65], v[180:183], v[216:219], v[62:65]
	global_load_lds_dwordx4 v244, s[40:41]
	ds_read_b128 v[146:149], v198
	v_mfma_f32_16x16x32_bf16 v[54:57], v[180:183], v[220:223], v[54:57]
	ds_read_b128 v[150:153], v198 offset:2048
	s_add_i32 m0, s45, 0x400
	v_mfma_f32_16x16x32_bf16 v[46:49], v[180:183], v[224:227], v[46:49]
	global_load_lds_dwordx4 v245, s[40:41]
	ds_read_b128 v[154:157], v198 offset:4096
	v_mfma_f32_16x16x32_bf16 v[38:41], v[180:183], v[240:243], v[38:41]
	ds_read_b128 v[158:161], v198 offset:6144
	s_add_i32 m0, s45, 0x800
	v_mfma_f32_16x16x32_bf16 v[58:61], v[184:187], v[216:219], v[58:61]
	global_load_lds_dwordx4 v246, s[40:41]
	ds_read_b128 v[164:167], v196
	v_mfma_f32_16x16x32_bf16 v[50:53], v[184:187], v[220:223], v[50:53]
	ds_read_b128 v[168:171], v196 offset:2048
	s_add_i32 m0, s45, 0xc00
	v_mfma_f32_16x16x32_bf16 v[42:45], v[184:187], v[224:227], v[42:45]
	global_load_lds_dwordx4 v247, s[40:41]
	ds_read_b128 v[172:175], v196 offset:4096
	v_mfma_f32_16x16x32_bf16 v[34:37], v[184:187], v[240:243], v[34:37]
	ds_read_b128 v[176:179], v196 offset:6144
	s_add_i32 m0, s45, 0x1000
	v_mfma_f32_16x16x32_bf16 v[30:33], v[188:191], v[216:219], v[30:33]
	global_load_lds_dwordx4 v248, s[40:41]
	v_mfma_f32_16x16x32_bf16 v[22:25], v[188:191], v[220:223], v[22:25]
	s_add_i32 m0, s45, 0x1400
	v_mfma_f32_16x16x32_bf16 v[14:17], v[188:191], v[224:227], v[14:17]
	global_load_lds_dwordx4 v249, s[40:41]
	v_mfma_f32_16x16x32_bf16 v[10:13], v[188:191], v[240:243], v[10:13]
	s_add_i32 m0, s45, 0x1800
	v_mfma_f32_16x16x32_bf16 v[26:29], v[192:195], v[216:219], v[26:29]
	global_load_lds_dwordx4 v250, s[40:41]
	v_mfma_f32_16x16x32_bf16 v[18:21], v[192:195], v[220:223], v[18:21]
	s_add_i32 m0, s45, 0x1c00
	v_mfma_f32_16x16x32_bf16 v[6:9], v[192:195], v[224:227], v[6:9]
	global_load_lds_dwordx4 v251, s[40:41]
	v_mfma_f32_16x16x32_bf16 v[2:5], v[192:195], v[240:243], v[2:5]
	s_add_u32 s40, s40, 0x80
	s_addc_u32 s41, s41, 0
	s_add_i32 s46, s46, 1
	s_cmp_lt_u32 s46, 7
	s_cbranch_scc1 .LgA_loop
	s_waitcnt lgkmcnt(0)
	v_mfma_f32_16x16x32_bf16 v[126:129], v[164:167], v[146:149], v[126:129]
	v_mfma_f32_16x16x32_bf16 v[118:121], v[164:167], v[150:153], v[118:121]
	ds_read_b128 v[180:183], v196 offset:8192
	v_mfma_f32_16x16x32_bf16 v[110:113], v[164:167], v[154:157], v[110:113]
	v_mfma_f32_16x16x32_bf16 v[102:105], v[164:167], v[158:161], v[102:105]
	v_mfma_f32_16x16x32_bf16 v[122:125], v[168:171], v[146:149], v[122:125]
	ds_read_b128 v[184:187], v196 offset:10240
	v_mfma_f32_16x16x32_bf16 v[114:117], v[168:171], v[150:153], v[114:117]
	v_mfma_f32_16x16x32_bf16 v[106:109], v[168:171], v[154:157], v[106:109]
	v_mfma_f32_16x16x32_bf16 v[98:101], v[168:171], v[158:161], v[98:101]
	ds_read_b128 v[188:191], v196 offset:12288
	v_mfma_f32_16x16x32_bf16 v[94:97], v[172:175], v[146:149], v[94:97]
	v_mfma_f32_16x16x32_bf16 v[86:89], v[172:175], v[150:153], v[86:89]
	v_mfma_f32_16x16x32_bf16 v[78:81], v[172:175], v[154:157], v[78:81]
	ds_read_b128 v[192:195], v196 offset:14336
	v_mfma_f32_16x16x32_bf16 v[70:73], v[172:175], v[158:161], v[70:73]
	v_mfma_f32_16x16x32_bf16 v[90:93], v[176:179], v[146:149], v[90:93]
	v_mfma_f32_16x16x32_bf16 v[82:85], v[176:179], v[150:153], v[82:85]
	v_mfma_f32_16x16x32_bf16 v[74:77], v[176:179], v[154:157], v[74:77]
	v_mfma_f32_16x16x32_bf16 v[66:69], v[176:179], v[158:161], v[66:69]
	s_waitcnt lgkmcnt(0)
	v_mfma_f32_16x16x32_bf16 v[62:65], v[180:183], v[146:149], v[62:65]
	ds_read_b128 v[216:219], v198 offset:1024
	v_mfma_f32_16x16x32_bf16 v[54:57], v[180:183], v[150:153], v[54:57]
	v_mfma_f32_16x16x32_bf16 v[46:49], v[180:183], v[154:157], v[46:49]
	ds_read_b128 v[220:223], v198 offset:3072
	v_mfma_f32_16x16x32_bf16 v[38:41], v[180:183], v[158:161], v[38:41]
	v_mfma_f32_16x16x32_bf16 v[58:61], v[184:187], v[146:149], v[58:61]
	ds_read_b128 v[224:227], v198 offset:5120
	v_mfma_f32_16x16x32_bf16 v[50:53], v[184:187], v[150:153], v[50:53]
	v_mfma_f32_16x16x32_bf16 v[42:45], v[184:187], v[154:157], v[42:45]
	ds_read_b128 v[240:243], v198 offset:7168
	v_mfma_f32_16x16x32_bf16 v[34:37], v[184:187], v[158:161], v[34:37]
	v_mfma_f32_16x16x32_bf16 v[30:33], v[188:191], v[146:149], v[30:33]
	ds_read_b128 v[164:167], v196 offset:1024
	v_mfma_f32_16x16x32_bf16 v[22:25], v[188:191], v[150:153], v[22:25]
	ds_read_b128 v[168:171], v196 offset:3072
	v_mfma_f32_16x16x32_bf16 v[14:17], v[188:191], v[154:157], v[14:17]
	ds_read_b128 v[172:175], v196 offset:5120
	v_mfma_f32_16x16x32_bf16 v[10:13], v[188:191], v[158:161], v[10:13]
	ds_read_b128 v[176:179], v196 offset:7168
	v_mfma_f32_16x16x32_bf16 v[26:29], v[192:195], v[146:149], v[26:29]
	v_mfma_f32_16x16x32_bf16 v[18:21], v[192:195], v[150:153], v[18:21]
	v_mfma_f32_16x16x32_bf16 v[6:9], v[192:195], v[154:157], v[6:9]
	v_mfma_f32_16x16x32_bf16 v[2:5], v[192:195], v[158:161], v[2:5]
	s_waitcnt lgkmcnt(0)
	v_mfma_f32_16x16x32_bf16 v[126:129], v[164:167], v[216:219], v[126:129]
	v_mfma_f32_16x16x32_bf16 v[118:121], v[164:167], v[220:223], v[118:121]
	ds_read_b128 v[180:183], v196 offset:9216
	v_mfma_f32_16x16x32_bf16 v[110:113], v[164:167], v[224:227], v[110:113]
	v_mfma_f32_16x16x32_bf16 v[102:105], v[164:167], v[240:243], v[102:105]
	v_mfma_f32_16x16x32_bf16 v[122:125], v[168:171], v[216:219], v[122:125]
	ds_read_b128 v[184:187], v196 offset:11264
	v_mfma_f32_16x16x32_bf16 v[114:117], v[168:171], v[220:223], v[114:117]
	v_mfma_f32_16x16x32_bf16 v[106:109], v[168:171], v[224:227], v[106:109]
	v_mfma_f32_16x16x32_bf16 v[98:101], v[168:171], v[240:243], v[98:101]
	ds_read_b128 v[188:191], v196 offset:13312
	v_mfma_f32_16x16x32_bf16 v[94:97], v[172:175], v[216:219], v[94:97]
	v_mfma_f32_16x16x32_bf16 v[86:89], v[172:175], v[220:223], v[86:89]
	v_mfma_f32_16x16x32_bf16 v[78:81], v[172:175], v[224:227], v[78:81]
	ds_read_b128 v[192:195], v196 offset:15360
	v_mfma_f32_16x16x32_bf16 v[70:73], v[172:175], v[240:243], v[70:73]
	v_mfma_f32_16x16x32_bf16 v[90:93], v[176:179], v[216:219], v[90:93]
	v_mfma_f32_16x16x32_bf16 v[82:85], v[176:179], v[220:223], v[82:85]
	v_mfma_f32_16x16x32_bf16 v[74:77], v[176:179], v[224:227], v[74:77]
	v_mfma_f32_16x16x32_bf16 v[66:69], v[176:179], v[240:243], v[66:69]
	s_waitcnt lgkmcnt(0)
	s_waitcnt vmcnt(0)
	s_barrier
; #define G_LDA(dst, ih, ks) _Pragma("unroll") for (int i = 0; i < 4; ++i) dst[i] = mk8(*(const u32x4*)(stage + ra + (((ih) * 4 + i) * 2 + (ks)) * 1024))
; #define G_LDB(dst, ks) _Pragma("unroll") for (int j = 0; j < 4; ++j) dst[j] = mk8(*(const u32x4*)(stage + TILE_B + rb + (j * 2 + (ks)) * 1024))
; #define G_MMA(ih, A, B) do { _Pragma("unroll") for (int i = 0; i < 4; ++i) _Pragma("unroll") for (int j = 0; j < 4; ++j) acc[(ih) * 4 + i][j] = MFMA16(A[i], B[j], acc[(ih) * 4 + i][j]); } while (0)
; DI void g_compute(const unsigned char* stage, int ra, int rb, f32x4 (&acc)[8][4]) {
;   bf16x8 b0[4], b1[4], a0[4], a1[4];
;   G_LDB(b0, 0); G_LDA(a0, 0, 0);
;   __builtin_amdgcn_sched_barrier(0);
;   G_LDA(a1, 1, 0);
;   G_MMA(0, a0, b0);
;   __builtin_amdgcn_sched_barrier(0);
;   G_LDB(b1, 1); G_LDA(a0, 0, 1);
;   G_MMA(1, a1, b0);
;   __builtin_amdgcn_sched_barrier(0);
;   G_LDA(a1, 1, 1);
;   G_MMA(0, a0, b1);
;   __builtin_amdgcn_sched_barrier(0);
;   G_MMA(1, a1, b1);
;   __builtin_amdgcn_sched_barrier(0);
; }
;     ...
;   for (int kt = 0; kt < KT; kt += 2) {
;     g_dma(base, off, (kt + 1) * kstep, buf1, w);
;     g_compute(buf0, ra, rb, acc);
;     asm volatile("s_waitcnt vmcnt(0)" ::: "memory");
;     __syncthreads();
;     const bool last = kt + 2 >= KT;
;     g_dma(last ? nbase : base, off, last ? 0 : (kt + 2) * kstep, buf0, w);
;     g_compute(buf1, ra, rb, acc);
;     asm volatile("s_waitcnt vmcnt(0)" ::: "memory");
;     __syncthreads();
	s_add_i32 m0, s44, 0x0
	v_mfma_f32_16x16x32_bf16 v[62:65], v[180:183], v[216:219], v[62:65]
	global_load_lds_dwordx4 v244, s[42:43]
	ds_read_b128 v[146:149], v199
	v_mfma_f32_16x16x32_bf16 v[54:57], v[180:183], v[220:223], v[54:57]
	ds_read_b128 v[150:153], v199 offset:2048
	s_add_i32 m0, s44, 0x400
	v_mfma_f32_16x16x32_bf16 v[46:49], v[180:183], v[224:227], v[46:49]
	global_load_lds_dwordx4 v245, s[42:43]
	ds_read_b128 v[154:157], v199 offset:4096
	v_mfma_f32_16x16x32_bf16 v[38:41], v[180:183], v[240:243], v[38:41]
	ds_read_b128 v[158:161], v199 offset:6144
	s_add_i32 m0, s44, 0x800
	v_mfma_f32_16x16x32_bf16 v[58:61], v[184:187], v[216:219], v[58:61]
	global_load_lds_dwordx4 v246, s[42:43]
	ds_read_b128 v[164:167], v197
	v_mfma_f32_16x16x32_bf16 v[50:53], v[184:187], v[220:223], v[50:53]
	ds_read_b128 v[168:171], v197 offset:2048
	s_add_i32 m0, s44, 0xc00
	v_mfma_f32_16x16x32_bf16 v[42:45], v[184:187], v[224:227], v[42:45]
	global_load_lds_dwordx4 v247, s[42:43]
	ds_read_b128 v[172:175], v197 offset:4096
	v_mfma_f32_16x16x32_bf16 v[34:37], v[184:187], v[240:243], v[34:37]
	ds_read_b128 v[176:179], v197 offset:6144
	s_add_i32 m0, s44, 0x1000
	v_mfma_f32_16x16x32_bf16 v[30:33], v[188:191], v[216:219], v[30:33]
	global_load_lds_dwordx4 v248, s[42:43]
	v_mfma_f32_16x16x32_bf16 v[22:25], v[188:191], v[220:223], v[22:25]
	s_add_i32 m0, s44, 0x1400
	v_mfma_f32_16x16x32_bf16 v[14:17], v[188:191], v[224:227], v[14:17]
	global_load_lds_dwordx4 v249, s[42:43]
	v_mfma_f32_16x16x32_bf16 v[10:13], v[188:191], v[240:243], v[10:13]
	s_add_i32 m0, s44, 0x1800
	v_mfma_f32_16x16x32_bf16 v[26:29], v[192:195], v[216:219], v[26:29]
	global_load_lds_dwordx4 v250, s[42:43]
	v_mfma_f32_16x16x32_bf16 v[18:21], v[192:195], v[220:223], v[18:21]
	s_add_i32 m0, s44, 0x1c00
	v_mfma_f32_16x16x32_bf16 v[6:9], v[192:195], v[224:227], v[6:9]
	global_load_lds_dwordx4 v251, s[42:43]
	v_mfma_f32_16x16x32_bf16 v[2:5], v[192:195], v[240:243], v[2:5]
	s_add_u32 s42, s42, 0x80
	s_addc_u32 s43, s43, 0
	s_waitcnt lgkmcnt(0)
	v_mfma_f32_16x16x32_bf16 v[126:129], v[164:167], v[146:149], v[126:129]
	v_mfma_f32_16x16x32_bf16 v[118:121], v[164:167], v[150:153], v[118:121]
	ds_read_b128 v[180:183], v197 offset:8192
	v_mfma_f32_16x16x32_bf16 v[110:113], v[164:167], v[154:157], v[110:113]
	v_mfma_f32_16x16x32_bf16 v[102:105], v[164:167], v[158:161], v[102:105]
	v_mfma_f32_16x16x32_bf16 v[122:125], v[168:171], v[146:149], v[122:125]
	ds_read_b128 v[184:187], v197 offset:10240
	v_mfma_f32_16x16x32_bf16 v[114:117], v[168:171], v[150:153], v[114:117]
	v_mfma_f32_16x16x32_bf16 v[106:109], v[168:171], v[154:157], v[106:109]
	v_mfma_f32_16x16x32_bf16 v[98:101], v[168:171], v[158:161], v[98:101]
	ds_read_b128 v[188:191], v197 offset:12288
	v_mfma_f32_16x16x32_bf16 v[94:97], v[172:175], v[146:149], v[94:97]
	v_mfma_f32_16x16x32_bf16 v[86:89], v[172:175], v[150:153], v[86:89]
	v_mfma_f32_16x16x32_bf16 v[78:81], v[172:175], v[154:157], v[78:81]
	ds_read_b128 v[192:195], v197 offset:14336
	v_mfma_f32_16x16x32_bf16 v[70:73], v[172:175], v[158:161], v[70:73]
	v_mfma_f32_16x16x32_bf16 v[90:93], v[176:179], v[146:149], v[90:93]
	v_mfma_f32_16x16x32_bf16 v[82:85], v[176:179], v[150:153], v[82:85]
	v_mfma_f32_16x16x32_bf16 v[74:77], v[176:179], v[154:157], v[74:77]
	v_mfma_f32_16x16x32_bf16 v[66:69], v[176:179], v[158:161], v[66:69]
	s_waitcnt lgkmcnt(0)
	v_mfma_f32_16x16x32_bf16 v[62:65], v[180:183], v[146:149], v[62:65]
	ds_read_b128 v[216:219], v199 offset:1024
	v_mfma_f32_16x16x32_bf16 v[54:57], v[180:183], v[150:153], v[54:57]
	v_mfma_f32_16x16x32_bf16 v[46:49], v[180:183], v[154:157], v[46:49]
	ds_read_b128 v[220:223], v199 offset:3072
	v_mfma_f32_16x16x32_bf16 v[38:41], v[180:183], v[158:161], v[38:41]
	v_mfma_f32_16x16x32_bf16 v[58:61], v[184:187], v[146:149], v[58:61]
	ds_read_b128 v[224:227], v199 offset:5120
	v_mfma_f32_16x16x32_bf16 v[50:53], v[184:187], v[150:153], v[50:53]
	v_mfma_f32_16x16x32_bf16 v[42:45], v[184:187], v[154:157], v[42:45]
	ds_read_b128 v[240:243], v199 offset:7168
	v_mfma_f32_16x16x32_bf16 v[34:37], v[184:187], v[158:161], v[34:37]
	v_mfma_f32_16x16x32_bf16 v[30:33], v[188:191], v[146:149], v[30:33]
	ds_read_b128 v[164:167], v197 offset:1024
	v_mfma_f32_16x16x32_bf16 v[22:25], v[188:191], v[150:153], v[22:25]
	ds_read_b128 v[168:171], v197 offset:3072
	v_mfma_f32_16x16x32_bf16 v[14:17], v[188:191], v[154:157], v[14:17]
	ds_read_b128 v[172:175], v197 offset:5120
	v_mfma_f32_16x16x32_bf16 v[10:13], v[188:191], v[158:161], v[10:13]
	ds_read_b128 v[176:179], v197 offset:7168
	v_mfma_f32_16x16x32_bf16 v[26:29], v[192:195], v[146:149], v[26:29]
	v_mfma_f32_16x16x32_bf16 v[18:21], v[192:195], v[150:153], v[18:21]
	v_mfma_f32_16x16x32_bf16 v[6:9], v[192:195], v[154:157], v[6:9]
	v_mfma_f32_16x16x32_bf16 v[2:5], v[192:195], v[158:161], v[2:5]
	s_waitcnt lgkmcnt(0)
	v_mfma_f32_16x16x32_bf16 v[126:129], v[164:167], v[216:219], v[126:129]
	v_mfma_f32_16x16x32_bf16 v[118:121], v[164:167], v[220:223], v[118:121]
	ds_read_b128 v[180:183], v197 offset:9216
	v_mfma_f32_16x16x32_bf16 v[110:113], v[164:167], v[224:227], v[110:113]
	v_mfma_f32_16x16x32_bf16 v[102:105], v[164:167], v[240:243], v[102:105]
	v_mfma_f32_16x16x32_bf16 v[122:125], v[168:171], v[216:219], v[122:125]
	ds_read_b128 v[184:187], v197 offset:11264
	v_mfma_f32_16x16x32_bf16 v[114:117], v[168:171], v[220:223], v[114:117]
	v_mfma_f32_16x16x32_bf16 v[106:109], v[168:171], v[224:227], v[106:109]
	v_mfma_f32_16x16x32_bf16 v[98:101], v[168:171], v[240:243], v[98:101]
	ds_read_b128 v[188:191], v197 offset:13312
	v_mfma_f32_16x16x32_bf16 v[94:97], v[172:175], v[216:219], v[94:97]
	v_mfma_f32_16x16x32_bf16 v[86:89], v[172:175], v[220:223], v[86:89]
	v_mfma_f32_16x16x32_bf16 v[78:81], v[172:175], v[224:227], v[78:81]
	ds_read_b128 v[192:195], v197 offset:15360
	v_mfma_f32_16x16x32_bf16 v[70:73], v[172:175], v[240:243], v[70:73]
	v_mfma_f32_16x16x32_bf16 v[90:93], v[176:179], v[216:219], v[90:93]
	v_mfma_f32_16x16x32_bf16 v[82:85], v[176:179], v[220:223], v[82:85]
	v_mfma_f32_16x16x32_bf16 v[74:77], v[176:179], v[224:227], v[74:77]
	v_mfma_f32_16x16x32_bf16 v[66:69], v[176:179], v[240:243], v[66:69]
	s_waitcnt lgkmcnt(0)
	s_waitcnt vmcnt(0)
	s_barrier
; DI unsigned pk2(float lo, float hi) { f32x2 v = {lo, hi}; bf16x2_t b = __builtin_convertvector(v, bf16x2_t); return __builtin_bit_cast(unsigned, b); }
; DI float sigmoidf_(float x) { return __builtin_amdgcn_rcpf(1.f + __builtin_amdgcn_exp2f(-1.44269504089f * x)); }
; DI float siluf_(float x) { return x * __builtin_amdgcn_rcpf(1.f + __builtin_amdgcn_exp2f(-1.44269504089f * x)); }
; DI void phaseA_epilogue(const Params& p, int layer, int mt, int nt, const f32x4 (&acc)[8][4], const float* rs_s) {
;     ...
;   const bool headtype = nt < 4 || (nt >= 6 && nt < 10);
;   const bool rot = nt == 6 || nt == 7 || nt == 9;
;     ...
;       bf16_t* dstb; int ldd, c0; bool sil;
;       if (nt < 6) { dstb = p.sbz(); ldd = 512; c0 = (nt - 4) * 256; sil = true; }
;       else if (nt < 12) { dstb = p.nz(); ldd = 512; c0 = (nt - 10) * 256; sil = true; }
;       else if (nt < 16) { dstb = p.ga(); ldd = 1024; c0 = (nt - 12) * 256; sil = false; }
;       else { dstb = p.gb(); ldd = 1024; c0 = (nt - 16) * 256; sil = false; }
;       bf16_t* dst = dstb + tok * ldd + c0 + wa * 128 + quad * 8;
; #pragma unroll
;       for (int ip = 0; ip < 4; ++ip) {
;         const f32x4 v0 = acc[2 * ip][j] * rs, v1 = acc[2 * ip + 1][j] * rs;
;         f32x4 o0, o1;
; #pragma unroll
;         for (int r = 0; r < 4; ++r) { o0[r] = sil ? siluf_(v0[r]) : sigmoidf_(v0[r]); o1[r] = sil ? siluf_(v1[r]) : sigmoidf_(v1[r]); }
;         *(u32x4*)(dst + ip * 32) = (u32x4){pk2(o0[0], o0[1]), pk2(o0[2], o0[3]), pk2(o1[0], o1[1]), pk2(o1[2], o1[3])};
;       }
	s_add_i32 m0, s45, 0x0
	v_mfma_f32_16x16x32_bf16 v[62:65], v[180:183], v[216:219], v[62:65]
	global_load_lds_dwordx4 v244, s[42:43]
	v_mfma_f32_16x16x32_bf16 v[54:57], v[180:183], v[220:223], v[54:57]
	s_add_i32 m0, s45, 0x400
	v_mfma_f32_16x16x32_bf16 v[46:49], v[180:183], v[224:227], v[46:49]
	global_load_lds_dwordx4 v245, s[42:43]
	v_mfma_f32_16x16x32_bf16 v[38:41], v[180:183], v[240:243], v[38:41]
	s_add_i32 m0, s45, 0x800
	v_mfma_f32_16x16x32_bf16 v[58:61], v[184:187], v[216:219], v[58:61]
	global_load_lds_dwordx4 v246, s[42:43]
	v_mfma_f32_16x16x32_bf16 v[50:53], v[184:187], v[220:223], v[50:53]
	s_add_i32 m0, s45, 0xc00
	v_mfma_f32_16x16x32_bf16 v[42:45], v[184:187], v[224:227], v[42:45]
	global_load_lds_dwordx4 v247, s[42:43]
	v_mfma_f32_16x16x32_bf16 v[34:37], v[184:187], v[240:243], v[34:37]
	s_add_i32 m0, s45, 0x1000
	v_mfma_f32_16x16x32_bf16 v[30:33], v[188:191], v[216:219], v[30:33]
	global_load_lds_dwordx4 v248, s[42:43]
	v_mfma_f32_16x16x32_bf16 v[22:25], v[188:191], v[220:223], v[22:25]
	s_add_i32 m0, s45, 0x1400
	v_mfma_f32_16x16x32_bf16 v[14:17], v[188:191], v[224:227], v[14:17]
	global_load_lds_dwordx4 v249, s[42:43]
	v_mfma_f32_16x16x32_bf16 v[10:13], v[188:191], v[240:243], v[10:13]
	s_add_i32 m0, s45, 0x1800
	v_mfma_f32_16x16x32_bf16 v[26:29], v[192:195], v[216:219], v[26:29]
	global_load_lds_dwordx4 v250, s[42:43]
	v_mfma_f32_16x16x32_bf16 v[18:21], v[192:195], v[220:223], v[18:21]
	s_add_i32 m0, s45, 0x1c00
	v_mfma_f32_16x16x32_bf16 v[6:9], v[192:195], v[224:227], v[6:9]
	global_load_lds_dwordx4 v251, s[42:43]
	v_mfma_f32_16x16x32_bf16 v[2:5], v[192:195], v[240:243], v[2:5]
	s_add_u32 s42, s42, 0x80
	s_addc_u32 s43, s43, 0
	v_readfirstlane_b32 s87, v202
	s_nop 0
	s_cmp_lg_u32 s87, 20
	s_cselect_b32 s87, 1, 0
	s_nop 7
	s_nop 3
	v_readfirstlane_b32 s36, v202
	s_nop 0
	s_cmp_lt_u32 s36, 4
	s_cbranch_scc1 .Lmy_eA_compiler
	s_cmp_lt_u32 s36, 6
	s_cbranch_scc1 .Lmy_eA_mine
	s_cmp_lt_u32 s36, 10
	s_cbranch_scc1 .Lmy_eA_compiler
	s_cmp_lt_u32 s36, 20
	s_cbranch_scc0 .Lmy_eA_compiler
.Lmy_eA_mine:
	s_cmp_lt_u32 s36, 6
	s_cbranch_scc0 .Lmy_eA_n1
	s_sub_u32 s40, s36, 4
	s_lshl_b32 s40, s40, 9
	s_add_u32 s40, s40, 0xc170000
	s_mov_b32 s41, 10
	s_branch .Lmy_eA_n9
.Lmy_eA_n1:
	s_cmp_lt_u32 s36, 12
	s_cbranch_scc0 .Lmy_eA_n2
	s_sub_u32 s40, s36, 10
	s_lshl_b32 s40, s40, 9
	s_add_u32 s40, s40, 0x13570000
	s_mov_b32 s41, 10
	s_branch .Lmy_eA_n9
.Lmy_eA_n2:
	s_cmp_lt_u32 s36, 16
	s_cbranch_scc0 .Lmy_eA_n3
	s_sub_u32 s40, s36, 12
	s_lshl_b32 s40, s40, 9
	s_add_u32 s40, s40, 0x15570000
	s_mov_b32 s41, 11
	s_branch .Lmy_eA_n9
.Lmy_eA_n3:
	s_sub_u32 s40, s36, 16
	s_lshl_b32 s40, s40, 9
	s_add_u32 s40, s40, 0x19570000
	s_mov_b32 s41, 11
.Lmy_eA_n9:
	s_add_u32 s42, s14, s40
	s_addc_u32 s43, s15, 0
	v_and_b32_e32 v146, 15, v210
	v_lshrrev_b32_e32 v147, 2, v146
	v_and_b32_e32 v146, 3, v146
	v_lshl_add_u32 v146, v147, 3, v146
	v_and_b32_e32 v147, 0xc0, v210
	v_add_u32_e32 v146, v146, v147
	v_lshlrev_b32_e32 v198, 2, v146
	v_add_u32_e32 v198, 0x20020, v198
	v_lshl_or_b32 v146, v162, 8, v146
	v_lshlrev_b32_e32 v158, s41, v146
	v_ashrrev_i32_e32 v147, 8, v210
	v_lshl_add_u32 v158, v147, 8, v158
	v_bfe_u32 v147, v210, 4, 2
	v_lshl_add_u32 v158, v147, 4, v158
	s_lshl_b32 s44, 4, s41
	v_add_u32_e32 v159, s44, v158
	s_lshl_b32 s44, 32, s41
	v_add_u32_e32 v160, s44, v158
	s_lshl_b32 s44, 36, s41
	v_add_u32_e32 v161, s44, v158
	ds_read_b32 v196, v198
	ds_read_b32 v197, v198 offset:16
	ds_read_b32 v146, v198 offset:128
	ds_read_b32 v147, v198 offset:144
	s_cmp_lt_u32 s36, 12
	s_cselect_b32 s45, 1, 0
	s_waitcnt lgkmcnt(0)
	v_mov_b32_e32 v216, v196
	v_pk_mul_f32 v[126:127], v[126:127], v[216:217] op_sel_hi:[1,0]
	v_pk_mul_f32 v[128:129], v[128:129], v[216:217] op_sel_hi:[1,0]
	v_pk_mul_f32 v[122:123], v[122:123], v[216:217] op_sel_hi:[1,0]
	v_pk_mul_f32 v[124:125], v[124:125], v[216:217] op_sel_hi:[1,0]
	v_pk_mul_f32 v[94:95], v[94:95], v[216:217] op_sel_hi:[1,0]
	v_pk_mul_f32 v[96:97], v[96:97], v[216:217] op_sel_hi:[1,0]
	v_pk_mul_f32 v[90:91], v[90:91], v[216:217] op_sel_hi:[1,0]
	v_pk_mul_f32 v[92:93], v[92:93], v[216:217] op_sel_hi:[1,0]
	v_mul_f32_e32 v164, 0xbfb8aa3b, v126
	v_mul_f32_e32 v165, 0xbfb8aa3b, v127
	v_mul_f32_e32 v166, 0xbfb8aa3b, v128
	v_mul_f32_e32 v167, 0xbfb8aa3b, v129
	v_mul_f32_e32 v168, 0xbfb8aa3b, v122
	v_mul_f32_e32 v169, 0xbfb8aa3b, v123
	v_mul_f32_e32 v170, 0xbfb8aa3b, v124
	v_mul_f32_e32 v171, 0xbfb8aa3b, v125
	v_mul_f32_e32 v172, 0xbfb8aa3b, v94
	v_mul_f32_e32 v173, 0xbfb8aa3b, v95
	v_mul_f32_e32 v174, 0xbfb8aa3b, v96
	v_mul_f32_e32 v175, 0xbfb8aa3b, v97
	v_mul_f32_e32 v176, 0xbfb8aa3b, v90
	v_mul_f32_e32 v177, 0xbfb8aa3b, v91
	v_mul_f32_e32 v178, 0xbfb8aa3b, v92
	v_mul_f32_e32 v179, 0xbfb8aa3b, v93
	v_exp_f32_e32 v164, v164
	v_exp_f32_e32 v165, v165
	v_exp_f32_e32 v166, v166
	v_exp_f32_e32 v167, v167
	v_exp_f32_e32 v168, v168
	v_exp_f32_e32 v169, v169
	v_exp_f32_e32 v170, v170
	v_exp_f32_e32 v171, v171
	v_exp_f32_e32 v172, v172
	v_exp_f32_e32 v173, v173
	v_exp_f32_e32 v174, v174
	v_exp_f32_e32 v175, v175
	v_exp_f32_e32 v176, v176
	v_exp_f32_e32 v177, v177
	v_exp_f32_e32 v178, v178
	v_exp_f32_e32 v179, v179
	v_add_f32_e32 v164, 1.0, v164
	v_add_f32_e32 v165, 1.0, v165
	v_add_f32_e32 v166, 1.0, v166
	v_add_f32_e32 v167, 1.0, v167
	v_add_f32_e32 v168, 1.0, v168
	v_add_f32_e32 v169, 1.0, v169
	v_add_f32_e32 v170, 1.0, v170
	v_add_f32_e32 v171, 1.0, v171
	v_add_f32_e32 v172, 1.0, v172
	v_add_f32_e32 v173, 1.0, v173
	v_add_f32_e32 v174, 1.0, v174
	v_add_f32_e32 v175, 1.0, v175
	v_add_f32_e32 v176, 1.0, v176
	v_add_f32_e32 v177, 1.0, v177
	v_add_f32_e32 v178, 1.0, v178
	v_add_f32_e32 v179, 1.0, v179
	v_rcp_f32_e32 v180, v164
	v_rcp_f32_e32 v181, v165
	v_rcp_f32_e32 v182, v166
	v_rcp_f32_e32 v183, v167
	v_rcp_f32_e32 v184, v168
	v_rcp_f32_e32 v185, v169
	v_rcp_f32_e32 v186, v170
	v_rcp_f32_e32 v187, v171
	v_rcp_f32_e32 v188, v172
	v_rcp_f32_e32 v189, v173
	v_rcp_f32_e32 v190, v174
	v_rcp_f32_e32 v191, v175
	v_rcp_f32_e32 v192, v176
	v_rcp_f32_e32 v193, v177
	v_rcp_f32_e32 v194, v178
	v_rcp_f32_e32 v195, v179
	s_cmp_eq_u32 s45, 0
	s_cbranch_scc1 .Lmy_eA_s00
	v_mul_f32_e32 v180, v126, v180
	v_mul_f32_e32 v181, v127, v181
	v_mul_f32_e32 v182, v128, v182
	v_mul_f32_e32 v183, v129, v183
	v_mul_f32_e32 v184, v122, v184
	v_mul_f32_e32 v185, v123, v185
	v_mul_f32_e32 v186, v124, v186
	v_mul_f32_e32 v187, v125, v187
	v_mul_f32_e32 v188, v94, v188
	v_mul_f32_e32 v189, v95, v189
	v_mul_f32_e32 v190, v96, v190
	v_mul_f32_e32 v191, v97, v191
	v_mul_f32_e32 v192, v90, v192
	v_mul_f32_e32 v193, v91, v193
	v_mul_f32_e32 v194, v92, v194
	v_mul_f32_e32 v195, v93, v195
; DI unsigned pk2(float lo, float hi) { f32x2 v = {lo, hi}; bf16x2_t b = __builtin_convertvector(v, bf16x2_t); return __builtin_bit_cast(unsigned, b); }
; DI float sigmoidf_(float x) { return __builtin_amdgcn_rcpf(1.f + __builtin_amdgcn_exp2f(-1.44269504089f * x)); }
; DI float siluf_(float x) { return x * __builtin_amdgcn_rcpf(1.f + __builtin_amdgcn_exp2f(-1.44269504089f * x)); }
; DI void phaseA_epilogue(const Params& p, int layer, int mt, int nt, const f32x4 (&acc)[8][4], const float* rs_s) {
;     ...
;       bf16_t* dstb; int ldd, c0; bool sil;
;       if (nt < 6) { dstb = p.sbz(); ldd = 512; c0 = (nt - 4) * 256; sil = true; }
;       else if (nt < 12) { dstb = p.nz(); ldd = 512; c0 = (nt - 10) * 256; sil = true; }
;       else if (nt < 16) { dstb = p.ga(); ldd = 1024; c0 = (nt - 12) * 256; sil = false; }
;       else { dstb = p.gb(); ldd = 1024; c0 = (nt - 16) * 256; sil = false; }
;       bf16_t* dst = dstb + tok * ldd + c0 + wa * 128 + quad * 8;
; #pragma unroll
;       for (int ip = 0; ip < 4; ++ip) {
;         const f32x4 v0 = acc[2 * ip][j] * rs, v1 = acc[2 * ip + 1][j] * rs;
;         f32x4 o0, o1;
; #pragma unroll
;         for (int r = 0; r < 4; ++r) { o0[r] = sil ? siluf_(v0[r]) : sigmoidf_(v0[r]); o1[r] = sil ? siluf_(v1[r]) : sigmoidf_(v1[r]); }
;         *(u32x4*)(dst + ip * 32) = (u32x4){pk2(o0[0], o0[1]), pk2(o0[2], o0[3]), pk2(o1[0], o1[1]), pk2(o1[2], o1[3])};
;       }
.Lmy_eA_s00:
	v_cvt_pk_bf16_f32 v150, v180, v181
	v_cvt_pk_bf16_f32 v151, v182, v183
	v_cvt_pk_bf16_f32 v152, v184, v185
	v_cvt_pk_bf16_f32 v153, v186, v187
	global_store_dwordx4 v158, v[150:153], s[42:43]
	v_cvt_pk_bf16_f32 v154, v188, v189
	v_cvt_pk_bf16_f32 v155, v190, v191
	v_cvt_pk_bf16_f32 v156, v192, v193
	v_cvt_pk_bf16_f32 v157, v194, v195
	global_store_dwordx4 v158, v[154:157], s[42:43] offset:64
	v_pk_mul_f32 v[62:63], v[62:63], v[216:217] op_sel_hi:[1,0]
	v_pk_mul_f32 v[64:65], v[64:65], v[216:217] op_sel_hi:[1,0]
	v_pk_mul_f32 v[58:59], v[58:59], v[216:217] op_sel_hi:[1,0]
	v_pk_mul_f32 v[60:61], v[60:61], v[216:217] op_sel_hi:[1,0]
	v_pk_mul_f32 v[30:31], v[30:31], v[216:217] op_sel_hi:[1,0]
	v_pk_mul_f32 v[32:33], v[32:33], v[216:217] op_sel_hi:[1,0]
	v_pk_mul_f32 v[26:27], v[26:27], v[216:217] op_sel_hi:[1,0]
	v_pk_mul_f32 v[28:29], v[28:29], v[216:217] op_sel_hi:[1,0]
	v_mul_f32_e32 v164, 0xbfb8aa3b, v62
	v_mul_f32_e32 v165, 0xbfb8aa3b, v63
	v_mul_f32_e32 v166, 0xbfb8aa3b, v64
	v_mul_f32_e32 v167, 0xbfb8aa3b, v65
	v_mul_f32_e32 v168, 0xbfb8aa3b, v58
	v_mul_f32_e32 v169, 0xbfb8aa3b, v59
	v_mul_f32_e32 v170, 0xbfb8aa3b, v60
	v_mul_f32_e32 v171, 0xbfb8aa3b, v61
	v_mul_f32_e32 v172, 0xbfb8aa3b, v30
	v_mul_f32_e32 v173, 0xbfb8aa3b, v31
	v_mul_f32_e32 v174, 0xbfb8aa3b, v32
	v_mul_f32_e32 v175, 0xbfb8aa3b, v33
	v_mul_f32_e32 v176, 0xbfb8aa3b, v26
	v_mul_f32_e32 v177, 0xbfb8aa3b, v27
	v_mul_f32_e32 v178, 0xbfb8aa3b, v28
	v_mul_f32_e32 v179, 0xbfb8aa3b, v29
	v_exp_f32_e32 v164, v164
	v_exp_f32_e32 v165, v165
	v_exp_f32_e32 v166, v166
	v_exp_f32_e32 v167, v167
	v_exp_f32_e32 v168, v168
	v_exp_f32_e32 v169, v169
	v_exp_f32_e32 v170, v170
	v_exp_f32_e32 v171, v171
	v_exp_f32_e32 v172, v172
	v_exp_f32_e32 v173, v173
	v_exp_f32_e32 v174, v174
	v_exp_f32_e32 v175, v175
	v_exp_f32_e32 v176, v176
	v_exp_f32_e32 v177, v177
	v_exp_f32_e32 v178, v178
	v_exp_f32_e32 v179, v179
	v_add_f32_e32 v164, 1.0, v164
	v_add_f32_e32 v165, 1.0, v165
	v_add_f32_e32 v166, 1.0, v166
	v_add_f32_e32 v167, 1.0, v167
	v_add_f32_e32 v168, 1.0, v168
	v_add_f32_e32 v169, 1.0, v169
	v_add_f32_e32 v170, 1.0, v170
	v_add_f32_e32 v171, 1.0, v171
	v_add_f32_e32 v172, 1.0, v172
	v_add_f32_e32 v173, 1.0, v173
	v_add_f32_e32 v174, 1.0, v174
	v_add_f32_e32 v175, 1.0, v175
	v_add_f32_e32 v176, 1.0, v176
	v_add_f32_e32 v177, 1.0, v177
	v_add_f32_e32 v178, 1.0, v178
	v_add_f32_e32 v179, 1.0, v179
	v_rcp_f32_e32 v180, v164
	v_rcp_f32_e32 v181, v165
	v_rcp_f32_e32 v182, v166
	v_rcp_f32_e32 v183, v167
	v_rcp_f32_e32 v184, v168
	v_rcp_f32_e32 v185, v169
	v_rcp_f32_e32 v186, v170
	v_rcp_f32_e32 v187, v171
	v_rcp_f32_e32 v188, v172
	v_rcp_f32_e32 v189, v173
	v_rcp_f32_e32 v190, v174
	v_rcp_f32_e32 v191, v175
	v_rcp_f32_e32 v192, v176
	v_rcp_f32_e32 v193, v177
	v_rcp_f32_e32 v194, v178
	v_rcp_f32_e32 v195, v179
	s_cmp_eq_u32 s45, 0
	s_cbranch_scc1 .Lmy_eA_s01
	v_mul_f32_e32 v180, v62, v180
	v_mul_f32_e32 v181, v63, v181
	v_mul_f32_e32 v182, v64, v182
	v_mul_f32_e32 v183, v65, v183
	v_mul_f32_e32 v184, v58, v184
	v_mul_f32_e32 v185, v59, v185
	v_mul_f32_e32 v186, v60, v186
	v_mul_f32_e32 v187, v61, v187
	v_mul_f32_e32 v188, v30, v188
	v_mul_f32_e32 v189, v31, v189
	v_mul_f32_e32 v190, v32, v190
	v_mul_f32_e32 v191, v33, v191
	v_mul_f32_e32 v192, v26, v192
	v_mul_f32_e32 v193, v27, v193
	v_mul_f32_e32 v194, v28, v194
	v_mul_f32_e32 v195, v29, v195
.Lmy_eA_s01:
	v_cvt_pk_bf16_f32 v150, v180, v181
	v_cvt_pk_bf16_f32 v151, v182, v183
	v_cvt_pk_bf16_f32 v152, v184, v185
	v_cvt_pk_bf16_f32 v153, v186, v187
	global_store_dwordx4 v158, v[150:153], s[42:43] offset:128
	v_cvt_pk_bf16_f32 v154, v188, v189
	v_cvt_pk_bf16_f32 v155, v190, v191
	v_cvt_pk_bf16_f32 v156, v192, v193
	v_cvt_pk_bf16_f32 v157, v194, v195
	global_store_dwordx4 v158, v[154:157], s[42:43] offset:192
	v_mov_b32_e32 v216, v197
	v_pk_mul_f32 v[118:119], v[118:119], v[216:217] op_sel_hi:[1,0]
	v_pk_mul_f32 v[120:121], v[120:121], v[216:217] op_sel_hi:[1,0]
	v_pk_mul_f32 v[114:115], v[114:115], v[216:217] op_sel_hi:[1,0]
	v_pk_mul_f32 v[116:117], v[116:117], v[216:217] op_sel_hi:[1,0]
	v_pk_mul_f32 v[86:87], v[86:87], v[216:217] op_sel_hi:[1,0]
	v_pk_mul_f32 v[88:89], v[88:89], v[216:217] op_sel_hi:[1,0]
	v_pk_mul_f32 v[82:83], v[82:83], v[216:217] op_sel_hi:[1,0]
	v_pk_mul_f32 v[84:85], v[84:85], v[216:217] op_sel_hi:[1,0]
	v_mul_f32_e32 v164, 0xbfb8aa3b, v118
	v_mul_f32_e32 v165, 0xbfb8aa3b, v119
	v_mul_f32_e32 v166, 0xbfb8aa3b, v120
	v_mul_f32_e32 v167, 0xbfb8aa3b, v121
	v_mul_f32_e32 v168, 0xbfb8aa3b, v114
	v_mul_f32_e32 v169, 0xbfb8aa3b, v115
	v_mul_f32_e32 v170, 0xbfb8aa3b, v116
	v_mul_f32_e32 v171, 0xbfb8aa3b, v117
	v_mul_f32_e32 v172, 0xbfb8aa3b, v86
	v_mul_f32_e32 v173, 0xbfb8aa3b, v87
	v_mul_f32_e32 v174, 0xbfb8aa3b, v88
	v_mul_f32_e32 v175, 0xbfb8aa3b, v89
	v_mul_f32_e32 v176, 0xbfb8aa3b, v82
	v_mul_f32_e32 v177, 0xbfb8aa3b, v83
	v_mul_f32_e32 v178, 0xbfb8aa3b, v84
	v_mul_f32_e32 v179, 0xbfb8aa3b, v85
	v_exp_f32_e32 v164, v164
	v_exp_f32_e32 v165, v165
	v_exp_f32_e32 v166, v166
	v_exp_f32_e32 v167, v167
	v_exp_f32_e32 v168, v168
	v_exp_f32_e32 v169, v169
	v_exp_f32_e32 v170, v170
	v_exp_f32_e32 v171, v171
	v_exp_f32_e32 v172, v172
	v_exp_f32_e32 v173, v173
	v_exp_f32_e32 v174, v174
	v_exp_f32_e32 v175, v175
	v_exp_f32_e32 v176, v176
	v_exp_f32_e32 v177, v177
	v_exp_f32_e32 v178, v178
	v_exp_f32_e32 v179, v179
	v_add_f32_e32 v164, 1.0, v164
	v_add_f32_e32 v165, 1.0, v165
	v_add_f32_e32 v166, 1.0, v166
	v_add_f32_e32 v167, 1.0, v167
	v_add_f32_e32 v168, 1.0, v168
	v_add_f32_e32 v169, 1.0, v169
	v_add_f32_e32 v170, 1.0, v170
	v_add_f32_e32 v171, 1.0, v171
	v_add_f32_e32 v172, 1.0, v172
	v_add_f32_e32 v173, 1.0, v173
	v_add_f32_e32 v174, 1.0, v174
	v_add_f32_e32 v175, 1.0, v175
	v_add_f32_e32 v176, 1.0, v176
	v_add_f32_e32 v177, 1.0, v177
	v_add_f32_e32 v178, 1.0, v178
	v_add_f32_e32 v179, 1.0, v179
	v_rcp_f32_e32 v180, v164
	v_rcp_f32_e32 v181, v165
	v_rcp_f32_e32 v182, v166
	v_rcp_f32_e32 v183, v167
	v_rcp_f32_e32 v184, v168
	v_rcp_f32_e32 v185, v169
	v_rcp_f32_e32 v186, v170
	v_rcp_f32_e32 v187, v171
	v_rcp_f32_e32 v188, v172
	v_rcp_f32_e32 v189, v173
	v_rcp_f32_e32 v190, v174
	v_rcp_f32_e32 v191, v175
	v_rcp_f32_e32 v192, v176
	v_rcp_f32_e32 v193, v177
	v_rcp_f32_e32 v194, v178
	v_rcp_f32_e32 v195, v179
	s_cmp_eq_u32 s45, 0
	s_cbranch_scc1 .Lmy_eA_s10
	v_mul_f32_e32 v180, v118, v180
	v_mul_f32_e32 v181, v119, v181
	v_mul_f32_e32 v182, v120, v182
	v_mul_f32_e32 v183, v121, v183
	v_mul_f32_e32 v184, v114, v184
	v_mul_f32_e32 v185, v115, v185
	v_mul_f32_e32 v186, v116, v186
	v_mul_f32_e32 v187, v117, v187
	v_mul_f32_e32 v188, v86, v188
	v_mul_f32_e32 v189, v87, v189
	v_mul_f32_e32 v190, v88, v190
	v_mul_f32_e32 v191, v89, v191
	v_mul_f32_e32 v192, v82, v192
	v_mul_f32_e32 v193, v83, v193
	v_mul_f32_e32 v194, v84, v194
	v_mul_f32_e32 v195, v85, v195
; DI unsigned pk2(float lo, float hi) { f32x2 v = {lo, hi}; bf16x2_t b = __builtin_convertvector(v, bf16x2_t); return __builtin_bit_cast(unsigned, b); }
; DI float sigmoidf_(float x) { return __builtin_amdgcn_rcpf(1.f + __builtin_amdgcn_exp2f(-1.44269504089f * x)); }
; DI float siluf_(float x) { return x * __builtin_amdgcn_rcpf(1.f + __builtin_amdgcn_exp2f(-1.44269504089f * x)); }
; DI void phaseA_epilogue(const Params& p, int layer, int mt, int nt, const f32x4 (&acc)[8][4], const float* rs_s) {
;     ...
;       bf16_t* dstb; int ldd, c0; bool sil;
;       if (nt < 6) { dstb = p.sbz(); ldd = 512; c0 = (nt - 4) * 256; sil = true; }
;       else if (nt < 12) { dstb = p.nz(); ldd = 512; c0 = (nt - 10) * 256; sil = true; }
;       else if (nt < 16) { dstb = p.ga(); ldd = 1024; c0 = (nt - 12) * 256; sil = false; }
;       else { dstb = p.gb(); ldd = 1024; c0 = (nt - 16) * 256; sil = false; }
;       bf16_t* dst = dstb + tok * ldd + c0 + wa * 128 + quad * 8;
; #pragma unroll
;       for (int ip = 0; ip < 4; ++ip) {
;         const f32x4 v0 = acc[2 * ip][j] * rs, v1 = acc[2 * ip + 1][j] * rs;
;         f32x4 o0, o1;
; #pragma unroll
;         for (int r = 0; r < 4; ++r) { o0[r] = sil ? siluf_(v0[r]) : sigmoidf_(v0[r]); o1[r] = sil ? siluf_(v1[r]) : sigmoidf_(v1[r]); }
;         *(u32x4*)(dst + ip * 32) = (u32x4){pk2(o0[0], o0[1]), pk2(o0[2], o0[3]), pk2(o1[0], o1[1]), pk2(o1[2], o1[3])};
;       }
.Lmy_eA_s10:
	v_cvt_pk_bf16_f32 v150, v180, v181
	v_cvt_pk_bf16_f32 v151, v182, v183
	v_cvt_pk_bf16_f32 v152, v184, v185
	v_cvt_pk_bf16_f32 v153, v186, v187
	global_store_dwordx4 v159, v[150:153], s[42:43]
	v_cvt_pk_bf16_f32 v154, v188, v189
	v_cvt_pk_bf16_f32 v155, v190, v191
	v_cvt_pk_bf16_f32 v156, v192, v193
	v_cvt_pk_bf16_f32 v157, v194, v195
	global_store_dwordx4 v159, v[154:157], s[42:43] offset:64
	v_pk_mul_f32 v[54:55], v[54:55], v[216:217] op_sel_hi:[1,0]
	v_pk_mul_f32 v[56:57], v[56:57], v[216:217] op_sel_hi:[1,0]
	v_pk_mul_f32 v[50:51], v[50:51], v[216:217] op_sel_hi:[1,0]
	v_pk_mul_f32 v[52:53], v[52:53], v[216:217] op_sel_hi:[1,0]
	v_pk_mul_f32 v[22:23], v[22:23], v[216:217] op_sel_hi:[1,0]
	v_pk_mul_f32 v[24:25], v[24:25], v[216:217] op_sel_hi:[1,0]
	v_pk_mul_f32 v[18:19], v[18:19], v[216:217] op_sel_hi:[1,0]
	v_pk_mul_f32 v[20:21], v[20:21], v[216:217] op_sel_hi:[1,0]
	v_mul_f32_e32 v164, 0xbfb8aa3b, v54
	v_mul_f32_e32 v165, 0xbfb8aa3b, v55
	v_mul_f32_e32 v166, 0xbfb8aa3b, v56
	v_mul_f32_e32 v167, 0xbfb8aa3b, v57
	v_mul_f32_e32 v168, 0xbfb8aa3b, v50
	v_mul_f32_e32 v169, 0xbfb8aa3b, v51
	v_mul_f32_e32 v170, 0xbfb8aa3b, v52
	v_mul_f32_e32 v171, 0xbfb8aa3b, v53
	v_mul_f32_e32 v172, 0xbfb8aa3b, v22
	v_mul_f32_e32 v173, 0xbfb8aa3b, v23
	v_mul_f32_e32 v174, 0xbfb8aa3b, v24
	v_mul_f32_e32 v175, 0xbfb8aa3b, v25
	v_mul_f32_e32 v176, 0xbfb8aa3b, v18
	v_mul_f32_e32 v177, 0xbfb8aa3b, v19
	v_mul_f32_e32 v178, 0xbfb8aa3b, v20
	v_mul_f32_e32 v179, 0xbfb8aa3b, v21
	v_exp_f32_e32 v164, v164
	v_exp_f32_e32 v165, v165
	v_exp_f32_e32 v166, v166
	v_exp_f32_e32 v167, v167
	v_exp_f32_e32 v168, v168
	v_exp_f32_e32 v169, v169
	v_exp_f32_e32 v170, v170
	v_exp_f32_e32 v171, v171
	v_exp_f32_e32 v172, v172
	v_exp_f32_e32 v173, v173
	v_exp_f32_e32 v174, v174
	v_exp_f32_e32 v175, v175
	v_exp_f32_e32 v176, v176
	v_exp_f32_e32 v177, v177
	v_exp_f32_e32 v178, v178
	v_exp_f32_e32 v179, v179
	v_add_f32_e32 v164, 1.0, v164
	v_add_f32_e32 v165, 1.0, v165
	v_add_f32_e32 v166, 1.0, v166
	v_add_f32_e32 v167, 1.0, v167
	v_add_f32_e32 v168, 1.0, v168
	v_add_f32_e32 v169, 1.0, v169
	v_add_f32_e32 v170, 1.0, v170
	v_add_f32_e32 v171, 1.0, v171
	v_add_f32_e32 v172, 1.0, v172
	v_add_f32_e32 v173, 1.0, v173
	v_add_f32_e32 v174, 1.0, v174
	v_add_f32_e32 v175, 1.0, v175
	v_add_f32_e32 v176, 1.0, v176
	v_add_f32_e32 v177, 1.0, v177
	v_add_f32_e32 v178, 1.0, v178
	v_add_f32_e32 v179, 1.0, v179
	v_rcp_f32_e32 v180, v164
	v_rcp_f32_e32 v181, v165
	v_rcp_f32_e32 v182, v166
	v_rcp_f32_e32 v183, v167
	v_rcp_f32_e32 v184, v168
	v_rcp_f32_e32 v185, v169
	v_rcp_f32_e32 v186, v170
	v_rcp_f32_e32 v187, v171
	v_rcp_f32_e32 v188, v172
	v_rcp_f32_e32 v189, v173
	v_rcp_f32_e32 v190, v174
	v_rcp_f32_e32 v191, v175
	v_rcp_f32_e32 v192, v176
	v_rcp_f32_e32 v193, v177
	v_rcp_f32_e32 v194, v178
	v_rcp_f32_e32 v195, v179
	s_cmp_eq_u32 s45, 0
	s_cbranch_scc1 .Lmy_eA_s11
	v_mul_f32_e32 v180, v54, v180
	v_mul_f32_e32 v181, v55, v181
	v_mul_f32_e32 v182, v56, v182
	v_mul_f32_e32 v183, v57, v183
	v_mul_f32_e32 v184, v50, v184
	v_mul_f32_e32 v185, v51, v185
	v_mul_f32_e32 v186, v52, v186
	v_mul_f32_e32 v187, v53, v187
	v_mul_f32_e32 v188, v22, v188
	v_mul_f32_e32 v189, v23, v189
	v_mul_f32_e32 v190, v24, v190
	v_mul_f32_e32 v191, v25, v191
	v_mul_f32_e32 v192, v18, v192
	v_mul_f32_e32 v193, v19, v193
	v_mul_f32_e32 v194, v20, v194
	v_mul_f32_e32 v195, v21, v195
.Lmy_eA_s11:
	v_cvt_pk_bf16_f32 v150, v180, v181
	v_cvt_pk_bf16_f32 v151, v182, v183
	v_cvt_pk_bf16_f32 v152, v184, v185
	v_cvt_pk_bf16_f32 v153, v186, v187
	global_store_dwordx4 v159, v[150:153], s[42:43] offset:128
	v_cvt_pk_bf16_f32 v154, v188, v189
	v_cvt_pk_bf16_f32 v155, v190, v191
	v_cvt_pk_bf16_f32 v156, v192, v193
	v_cvt_pk_bf16_f32 v157, v194, v195
	global_store_dwordx4 v159, v[154:157], s[42:43] offset:192
	v_mov_b32_e32 v216, v146
	v_pk_mul_f32 v[110:111], v[110:111], v[216:217] op_sel_hi:[1,0]
	v_pk_mul_f32 v[112:113], v[112:113], v[216:217] op_sel_hi:[1,0]
	v_pk_mul_f32 v[106:107], v[106:107], v[216:217] op_sel_hi:[1,0]
	v_pk_mul_f32 v[108:109], v[108:109], v[216:217] op_sel_hi:[1,0]
	v_pk_mul_f32 v[78:79], v[78:79], v[216:217] op_sel_hi:[1,0]
	v_pk_mul_f32 v[80:81], v[80:81], v[216:217] op_sel_hi:[1,0]
	v_pk_mul_f32 v[74:75], v[74:75], v[216:217] op_sel_hi:[1,0]
	v_pk_mul_f32 v[76:77], v[76:77], v[216:217] op_sel_hi:[1,0]
	v_mul_f32_e32 v164, 0xbfb8aa3b, v110
	v_mul_f32_e32 v165, 0xbfb8aa3b, v111
	v_mul_f32_e32 v166, 0xbfb8aa3b, v112
	v_mul_f32_e32 v167, 0xbfb8aa3b, v113
	v_mul_f32_e32 v168, 0xbfb8aa3b, v106
	v_mul_f32_e32 v169, 0xbfb8aa3b, v107
	v_mul_f32_e32 v170, 0xbfb8aa3b, v108
	v_mul_f32_e32 v171, 0xbfb8aa3b, v109
	v_mul_f32_e32 v172, 0xbfb8aa3b, v78
	v_mul_f32_e32 v173, 0xbfb8aa3b, v79
	v_mul_f32_e32 v174, 0xbfb8aa3b, v80
	v_mul_f32_e32 v175, 0xbfb8aa3b, v81
	v_mul_f32_e32 v176, 0xbfb8aa3b, v74
	v_mul_f32_e32 v177, 0xbfb8aa3b, v75
	v_mul_f32_e32 v178, 0xbfb8aa3b, v76
	v_mul_f32_e32 v179, 0xbfb8aa3b, v77
	v_exp_f32_e32 v164, v164
	v_exp_f32_e32 v165, v165
	v_exp_f32_e32 v166, v166
	v_exp_f32_e32 v167, v167
	v_exp_f32_e32 v168, v168
	v_exp_f32_e32 v169, v169
	v_exp_f32_e32 v170, v170
	v_exp_f32_e32 v171, v171
	v_exp_f32_e32 v172, v172
	v_exp_f32_e32 v173, v173
	v_exp_f32_e32 v174, v174
	v_exp_f32_e32 v175, v175
	v_exp_f32_e32 v176, v176
	v_exp_f32_e32 v177, v177
	v_exp_f32_e32 v178, v178
	v_exp_f32_e32 v179, v179
	v_add_f32_e32 v164, 1.0, v164
	v_add_f32_e32 v165, 1.0, v165
	v_add_f32_e32 v166, 1.0, v166
	v_add_f32_e32 v167, 1.0, v167
	v_add_f32_e32 v168, 1.0, v168
	v_add_f32_e32 v169, 1.0, v169
	v_add_f32_e32 v170, 1.0, v170
	v_add_f32_e32 v171, 1.0, v171
	v_add_f32_e32 v172, 1.0, v172
	v_add_f32_e32 v173, 1.0, v173
	v_add_f32_e32 v174, 1.0, v174
	v_add_f32_e32 v175, 1.0, v175
	v_add_f32_e32 v176, 1.0, v176
	v_add_f32_e32 v177, 1.0, v177
	v_add_f32_e32 v178, 1.0, v178
	v_add_f32_e32 v179, 1.0, v179
	v_rcp_f32_e32 v180, v164
	v_rcp_f32_e32 v181, v165
	v_rcp_f32_e32 v182, v166
	v_rcp_f32_e32 v183, v167
	v_rcp_f32_e32 v184, v168
	v_rcp_f32_e32 v185, v169
	v_rcp_f32_e32 v186, v170
	v_rcp_f32_e32 v187, v171
	v_rcp_f32_e32 v188, v172
	v_rcp_f32_e32 v189, v173
	v_rcp_f32_e32 v190, v174
	v_rcp_f32_e32 v191, v175
	v_rcp_f32_e32 v192, v176
	v_rcp_f32_e32 v193, v177
	v_rcp_f32_e32 v194, v178
	v_rcp_f32_e32 v195, v179
	s_cmp_eq_u32 s45, 0
	s_cbranch_scc1 .Lmy_eA_s20
	v_mul_f32_e32 v180, v110, v180
	v_mul_f32_e32 v181, v111, v181
	v_mul_f32_e32 v182, v112, v182
	v_mul_f32_e32 v183, v113, v183
	v_mul_f32_e32 v184, v106, v184
	v_mul_f32_e32 v185, v107, v185
	v_mul_f32_e32 v186, v108, v186
	v_mul_f32_e32 v187, v109, v187
	v_mul_f32_e32 v188, v78, v188
	v_mul_f32_e32 v189, v79, v189
	v_mul_f32_e32 v190, v80, v190
	v_mul_f32_e32 v191, v81, v191
	v_mul_f32_e32 v192, v74, v192
	v_mul_f32_e32 v193, v75, v193
	v_mul_f32_e32 v194, v76, v194
	v_mul_f32_e32 v195, v77, v195
; DI unsigned pk2(float lo, float hi) { f32x2 v = {lo, hi}; bf16x2_t b = __builtin_convertvector(v, bf16x2_t); return __builtin_bit_cast(unsigned, b); }
; DI float sigmoidf_(float x) { return __builtin_amdgcn_rcpf(1.f + __builtin_amdgcn_exp2f(-1.44269504089f * x)); }
; DI float siluf_(float x) { return x * __builtin_amdgcn_rcpf(1.f + __builtin_amdgcn_exp2f(-1.44269504089f * x)); }
; DI void phaseA_epilogue(const Params& p, int layer, int mt, int nt, const f32x4 (&acc)[8][4], const float* rs_s) {
;     ...
;       bf16_t* dstb; int ldd, c0; bool sil;
;       if (nt < 6) { dstb = p.sbz(); ldd = 512; c0 = (nt - 4) * 256; sil = true; }
;       else if (nt < 12) { dstb = p.nz(); ldd = 512; c0 = (nt - 10) * 256; sil = true; }
;       else if (nt < 16) { dstb = p.ga(); ldd = 1024; c0 = (nt - 12) * 256; sil = false; }
;       else { dstb = p.gb(); ldd = 1024; c0 = (nt - 16) * 256; sil = false; }
;       bf16_t* dst = dstb + tok * ldd + c0 + wa * 128 + quad * 8;
; #pragma unroll
;       for (int ip = 0; ip < 4; ++ip) {
;         const f32x4 v0 = acc[2 * ip][j] * rs, v1 = acc[2 * ip + 1][j] * rs;
;         f32x4 o0, o1;
; #pragma unroll
;         for (int r = 0; r < 4; ++r) { o0[r] = sil ? siluf_(v0[r]) : sigmoidf_(v0[r]); o1[r] = sil ? siluf_(v1[r]) : sigmoidf_(v1[r]); }
;         *(u32x4*)(dst + ip * 32) = (u32x4){pk2(o0[0], o0[1]), pk2(o0[2], o0[3]), pk2(o1[0], o1[1]), pk2(o1[2], o1[3])};
;       }
.Lmy_eA_s20:
	v_cvt_pk_bf16_f32 v150, v180, v181
	v_cvt_pk_bf16_f32 v151, v182, v183
	v_cvt_pk_bf16_f32 v152, v184, v185
	v_cvt_pk_bf16_f32 v153, v186, v187
	global_store_dwordx4 v160, v[150:153], s[42:43]
	v_cvt_pk_bf16_f32 v154, v188, v189
	v_cvt_pk_bf16_f32 v155, v190, v191
	v_cvt_pk_bf16_f32 v156, v192, v193
	v_cvt_pk_bf16_f32 v157, v194, v195
	global_store_dwordx4 v160, v[154:157], s[42:43] offset:64
	v_pk_mul_f32 v[46:47], v[46:47], v[216:217] op_sel_hi:[1,0]
	v_pk_mul_f32 v[48:49], v[48:49], v[216:217] op_sel_hi:[1,0]
	v_pk_mul_f32 v[42:43], v[42:43], v[216:217] op_sel_hi:[1,0]
	v_pk_mul_f32 v[44:45], v[44:45], v[216:217] op_sel_hi:[1,0]
	v_pk_mul_f32 v[14:15], v[14:15], v[216:217] op_sel_hi:[1,0]
	v_pk_mul_f32 v[16:17], v[16:17], v[216:217] op_sel_hi:[1,0]
	v_pk_mul_f32 v[6:7], v[6:7], v[216:217] op_sel_hi:[1,0]
	v_pk_mul_f32 v[8:9], v[8:9], v[216:217] op_sel_hi:[1,0]
	v_mul_f32_e32 v164, 0xbfb8aa3b, v46
	v_mul_f32_e32 v165, 0xbfb8aa3b, v47
	v_mul_f32_e32 v166, 0xbfb8aa3b, v48
	v_mul_f32_e32 v167, 0xbfb8aa3b, v49
	v_mul_f32_e32 v168, 0xbfb8aa3b, v42
	v_mul_f32_e32 v169, 0xbfb8aa3b, v43
	v_mul_f32_e32 v170, 0xbfb8aa3b, v44
	v_mul_f32_e32 v171, 0xbfb8aa3b, v45
	v_mul_f32_e32 v172, 0xbfb8aa3b, v14
	v_mul_f32_e32 v173, 0xbfb8aa3b, v15
	v_mul_f32_e32 v174, 0xbfb8aa3b, v16
	v_mul_f32_e32 v175, 0xbfb8aa3b, v17
	v_mul_f32_e32 v176, 0xbfb8aa3b, v6
	v_mul_f32_e32 v177, 0xbfb8aa3b, v7
	v_mul_f32_e32 v178, 0xbfb8aa3b, v8
	v_mul_f32_e32 v179, 0xbfb8aa3b, v9
	v_exp_f32_e32 v164, v164
	v_exp_f32_e32 v165, v165
	v_exp_f32_e32 v166, v166
	v_exp_f32_e32 v167, v167
	v_exp_f32_e32 v168, v168
	v_exp_f32_e32 v169, v169
	v_exp_f32_e32 v170, v170
	v_exp_f32_e32 v171, v171
	v_exp_f32_e32 v172, v172
	v_exp_f32_e32 v173, v173
	v_exp_f32_e32 v174, v174
	v_exp_f32_e32 v175, v175
	v_exp_f32_e32 v176, v176
	v_exp_f32_e32 v177, v177
	v_exp_f32_e32 v178, v178
	v_exp_f32_e32 v179, v179
	v_add_f32_e32 v164, 1.0, v164
	v_add_f32_e32 v165, 1.0, v165
	v_add_f32_e32 v166, 1.0, v166
	v_add_f32_e32 v167, 1.0, v167
	v_add_f32_e32 v168, 1.0, v168
	v_add_f32_e32 v169, 1.0, v169
	v_add_f32_e32 v170, 1.0, v170
	v_add_f32_e32 v171, 1.0, v171
	v_add_f32_e32 v172, 1.0, v172
	v_add_f32_e32 v173, 1.0, v173
	v_add_f32_e32 v174, 1.0, v174
	v_add_f32_e32 v175, 1.0, v175
	v_add_f32_e32 v176, 1.0, v176
	v_add_f32_e32 v177, 1.0, v177
	v_add_f32_e32 v178, 1.0, v178
	v_add_f32_e32 v179, 1.0, v179
	v_rcp_f32_e32 v180, v164
	v_rcp_f32_e32 v181, v165
	v_rcp_f32_e32 v182, v166
	v_rcp_f32_e32 v183, v167
	v_rcp_f32_e32 v184, v168
	v_rcp_f32_e32 v185, v169
	v_rcp_f32_e32 v186, v170
	v_rcp_f32_e32 v187, v171
	v_rcp_f32_e32 v188, v172
	v_rcp_f32_e32 v189, v173
	v_rcp_f32_e32 v190, v174
	v_rcp_f32_e32 v191, v175
	v_rcp_f32_e32 v192, v176
	v_rcp_f32_e32 v193, v177
	v_rcp_f32_e32 v194, v178
	v_rcp_f32_e32 v195, v179
	s_cmp_eq_u32 s45, 0
	s_cbranch_scc1 .Lmy_eA_s21
	v_mul_f32_e32 v180, v46, v180
	v_mul_f32_e32 v181, v47, v181
	v_mul_f32_e32 v182, v48, v182
	v_mul_f32_e32 v183, v49, v183
	v_mul_f32_e32 v184, v42, v184
	v_mul_f32_e32 v185, v43, v185
	v_mul_f32_e32 v186, v44, v186
	v_mul_f32_e32 v187, v45, v187
	v_mul_f32_e32 v188, v14, v188
	v_mul_f32_e32 v189, v15, v189
	v_mul_f32_e32 v190, v16, v190
	v_mul_f32_e32 v191, v17, v191
	v_mul_f32_e32 v192, v6, v192
	v_mul_f32_e32 v193, v7, v193
	v_mul_f32_e32 v194, v8, v194
	v_mul_f32_e32 v195, v9, v195
.Lmy_eA_s21:
	v_cvt_pk_bf16_f32 v150, v180, v181
	v_cvt_pk_bf16_f32 v151, v182, v183
	v_cvt_pk_bf16_f32 v152, v184, v185
	v_cvt_pk_bf16_f32 v153, v186, v187
	global_store_dwordx4 v160, v[150:153], s[42:43] offset:128
	v_cvt_pk_bf16_f32 v154, v188, v189
	v_cvt_pk_bf16_f32 v155, v190, v191
	v_cvt_pk_bf16_f32 v156, v192, v193
	v_cvt_pk_bf16_f32 v157, v194, v195
	global_store_dwordx4 v160, v[154:157], s[42:43] offset:192
	v_mov_b32_e32 v216, v147
	v_pk_mul_f32 v[102:103], v[102:103], v[216:217] op_sel_hi:[1,0]
	v_pk_mul_f32 v[104:105], v[104:105], v[216:217] op_sel_hi:[1,0]
	v_pk_mul_f32 v[98:99], v[98:99], v[216:217] op_sel_hi:[1,0]
	v_pk_mul_f32 v[100:101], v[100:101], v[216:217] op_sel_hi:[1,0]
	v_pk_mul_f32 v[70:71], v[70:71], v[216:217] op_sel_hi:[1,0]
	v_pk_mul_f32 v[72:73], v[72:73], v[216:217] op_sel_hi:[1,0]
	v_pk_mul_f32 v[66:67], v[66:67], v[216:217] op_sel_hi:[1,0]
	v_pk_mul_f32 v[68:69], v[68:69], v[216:217] op_sel_hi:[1,0]
	v_mul_f32_e32 v164, 0xbfb8aa3b, v102
	v_mul_f32_e32 v165, 0xbfb8aa3b, v103
	v_mul_f32_e32 v166, 0xbfb8aa3b, v104
	v_mul_f32_e32 v167, 0xbfb8aa3b, v105
	v_mul_f32_e32 v168, 0xbfb8aa3b, v98
	v_mul_f32_e32 v169, 0xbfb8aa3b, v99
	v_mul_f32_e32 v170, 0xbfb8aa3b, v100
	v_mul_f32_e32 v171, 0xbfb8aa3b, v101
	v_mul_f32_e32 v172, 0xbfb8aa3b, v70
	v_mul_f32_e32 v173, 0xbfb8aa3b, v71
	v_mul_f32_e32 v174, 0xbfb8aa3b, v72
	v_mul_f32_e32 v175, 0xbfb8aa3b, v73
	v_mul_f32_e32 v176, 0xbfb8aa3b, v66
	v_mul_f32_e32 v177, 0xbfb8aa3b, v67
	v_mul_f32_e32 v178, 0xbfb8aa3b, v68
	v_mul_f32_e32 v179, 0xbfb8aa3b, v69
	v_exp_f32_e32 v164, v164
	v_exp_f32_e32 v165, v165
	v_exp_f32_e32 v166, v166
	v_exp_f32_e32 v167, v167
	v_exp_f32_e32 v168, v168
	v_exp_f32_e32 v169, v169
	v_exp_f32_e32 v170, v170
	v_exp_f32_e32 v171, v171
	v_exp_f32_e32 v172, v172
	v_exp_f32_e32 v173, v173
	v_exp_f32_e32 v174, v174
	v_exp_f32_e32 v175, v175
	v_exp_f32_e32 v176, v176
	v_exp_f32_e32 v177, v177
	v_exp_f32_e32 v178, v178
	v_exp_f32_e32 v179, v179
	v_add_f32_e32 v164, 1.0, v164
	v_add_f32_e32 v165, 1.0, v165
	v_add_f32_e32 v166, 1.0, v166
	v_add_f32_e32 v167, 1.0, v167
	v_add_f32_e32 v168, 1.0, v168
	v_add_f32_e32 v169, 1.0, v169
	v_add_f32_e32 v170, 1.0, v170
	v_add_f32_e32 v171, 1.0, v171
	v_add_f32_e32 v172, 1.0, v172
	v_add_f32_e32 v173, 1.0, v173
	v_add_f32_e32 v174, 1.0, v174
	v_add_f32_e32 v175, 1.0, v175
	v_add_f32_e32 v176, 1.0, v176
	v_add_f32_e32 v177, 1.0, v177
	v_add_f32_e32 v178, 1.0, v178
	v_add_f32_e32 v179, 1.0, v179
	v_rcp_f32_e32 v180, v164
	v_rcp_f32_e32 v181, v165
	v_rcp_f32_e32 v182, v166
	v_rcp_f32_e32 v183, v167
	v_rcp_f32_e32 v184, v168
	v_rcp_f32_e32 v185, v169
	v_rcp_f32_e32 v186, v170
	v_rcp_f32_e32 v187, v171
	v_rcp_f32_e32 v188, v172
	v_rcp_f32_e32 v189, v173
	v_rcp_f32_e32 v190, v174
	v_rcp_f32_e32 v191, v175
	v_rcp_f32_e32 v192, v176
	v_rcp_f32_e32 v193, v177
	v_rcp_f32_e32 v194, v178
	v_rcp_f32_e32 v195, v179
	s_cmp_eq_u32 s45, 0
	s_cbranch_scc1 .Lmy_eA_s30
	v_mul_f32_e32 v180, v102, v180
	v_mul_f32_e32 v181, v103, v181
	v_mul_f32_e32 v182, v104, v182
	v_mul_f32_e32 v183, v105, v183
	v_mul_f32_e32 v184, v98, v184
	v_mul_f32_e32 v185, v99, v185
	v_mul_f32_e32 v186, v100, v186
	v_mul_f32_e32 v187, v101, v187
	v_mul_f32_e32 v188, v70, v188
	v_mul_f32_e32 v189, v71, v189
	v_mul_f32_e32 v190, v72, v190
	v_mul_f32_e32 v191, v73, v191
	v_mul_f32_e32 v192, v66, v192
	v_mul_f32_e32 v193, v67, v193
	v_mul_f32_e32 v194, v68, v194
	v_mul_f32_e32 v195, v69, v195
; DI unsigned pk2(float lo, float hi) { f32x2 v = {lo, hi}; bf16x2_t b = __builtin_convertvector(v, bf16x2_t); return __builtin_bit_cast(unsigned, b); }
; DI float sigmoidf_(float x) { return __builtin_amdgcn_rcpf(1.f + __builtin_amdgcn_exp2f(-1.44269504089f * x)); }
; DI float siluf_(float x) { return x * __builtin_amdgcn_rcpf(1.f + __builtin_amdgcn_exp2f(-1.44269504089f * x)); }
; DI void phaseA_epilogue(const Params& p, int layer, int mt, int nt, const f32x4 (&acc)[8][4], const float* rs_s) {
;     ...
;       bf16_t* dstb; int ldd, c0; bool sil;
;       if (nt < 6) { dstb = p.sbz(); ldd = 512; c0 = (nt - 4) * 256; sil = true; }
;       else if (nt < 12) { dstb = p.nz(); ldd = 512; c0 = (nt - 10) * 256; sil = true; }
;       else if (nt < 16) { dstb = p.ga(); ldd = 1024; c0 = (nt - 12) * 256; sil = false; }
;       else { dstb = p.gb(); ldd = 1024; c0 = (nt - 16) * 256; sil = false; }
;       bf16_t* dst = dstb + tok * ldd + c0 + wa * 128 + quad * 8;
; #pragma unroll
;       for (int ip = 0; ip < 4; ++ip) {
;         const f32x4 v0 = acc[2 * ip][j] * rs, v1 = acc[2 * ip + 1][j] * rs;
;         f32x4 o0, o1;
; #pragma unroll
;         for (int r = 0; r < 4; ++r) { o0[r] = sil ? siluf_(v0[r]) : sigmoidf_(v0[r]); o1[r] = sil ? siluf_(v1[r]) : sigmoidf_(v1[r]); }
;         *(u32x4*)(dst + ip * 32) = (u32x4){pk2(o0[0], o0[1]), pk2(o0[2], o0[3]), pk2(o1[0], o1[1]), pk2(o1[2], o1[3])};
;       }
.Lmy_eA_s30:
	v_cvt_pk_bf16_f32 v150, v180, v181
	v_cvt_pk_bf16_f32 v151, v182, v183
	v_cvt_pk_bf16_f32 v152, v184, v185
	v_cvt_pk_bf16_f32 v153, v186, v187
	global_store_dwordx4 v161, v[150:153], s[42:43]
	v_cvt_pk_bf16_f32 v154, v188, v189
	v_cvt_pk_bf16_f32 v155, v190, v191
	v_cvt_pk_bf16_f32 v156, v192, v193
	v_cvt_pk_bf16_f32 v157, v194, v195
	global_store_dwordx4 v161, v[154:157], s[42:43] offset:64
	v_pk_mul_f32 v[38:39], v[38:39], v[216:217] op_sel_hi:[1,0]
	v_pk_mul_f32 v[40:41], v[40:41], v[216:217] op_sel_hi:[1,0]
	v_pk_mul_f32 v[34:35], v[34:35], v[216:217] op_sel_hi:[1,0]
	v_pk_mul_f32 v[36:37], v[36:37], v[216:217] op_sel_hi:[1,0]
	v_pk_mul_f32 v[10:11], v[10:11], v[216:217] op_sel_hi:[1,0]
	v_pk_mul_f32 v[12:13], v[12:13], v[216:217] op_sel_hi:[1,0]
	v_pk_mul_f32 v[2:3], v[2:3], v[216:217] op_sel_hi:[1,0]
	v_pk_mul_f32 v[4:5], v[4:5], v[216:217] op_sel_hi:[1,0]
	v_mul_f32_e32 v164, 0xbfb8aa3b, v38
	v_mul_f32_e32 v165, 0xbfb8aa3b, v39
	v_mul_f32_e32 v166, 0xbfb8aa3b, v40
	v_mul_f32_e32 v167, 0xbfb8aa3b, v41
	v_mul_f32_e32 v168, 0xbfb8aa3b, v34
	v_mul_f32_e32 v169, 0xbfb8aa3b, v35
	v_mul_f32_e32 v170, 0xbfb8aa3b, v36
	v_mul_f32_e32 v171, 0xbfb8aa3b, v37
	v_mul_f32_e32 v172, 0xbfb8aa3b, v10
	v_mul_f32_e32 v173, 0xbfb8aa3b, v11
	v_mul_f32_e32 v174, 0xbfb8aa3b, v12
	v_mul_f32_e32 v175, 0xbfb8aa3b, v13
	v_mul_f32_e32 v176, 0xbfb8aa3b, v2
	v_mul_f32_e32 v177, 0xbfb8aa3b, v3
	v_mul_f32_e32 v178, 0xbfb8aa3b, v4
	v_mul_f32_e32 v179, 0xbfb8aa3b, v5
	v_exp_f32_e32 v164, v164
	v_exp_f32_e32 v165, v165
	v_exp_f32_e32 v166, v166
	v_exp_f32_e32 v167, v167
	v_exp_f32_e32 v168, v168
	v_exp_f32_e32 v169, v169
	v_exp_f32_e32 v170, v170
	v_exp_f32_e32 v171, v171
	v_exp_f32_e32 v172, v172
	v_exp_f32_e32 v173, v173
	v_exp_f32_e32 v174, v174
	v_exp_f32_e32 v175, v175
	v_exp_f32_e32 v176, v176
	v_exp_f32_e32 v177, v177
	v_exp_f32_e32 v178, v178
	v_exp_f32_e32 v179, v179
	v_add_f32_e32 v164, 1.0, v164
	v_add_f32_e32 v165, 1.0, v165
	v_add_f32_e32 v166, 1.0, v166
	v_add_f32_e32 v167, 1.0, v167
	v_add_f32_e32 v168, 1.0, v168
	v_add_f32_e32 v169, 1.0, v169
	v_add_f32_e32 v170, 1.0, v170
	v_add_f32_e32 v171, 1.0, v171
	v_add_f32_e32 v172, 1.0, v172
	v_add_f32_e32 v173, 1.0, v173
	v_add_f32_e32 v174, 1.0, v174
	v_add_f32_e32 v175, 1.0, v175
	v_add_f32_e32 v176, 1.0, v176
	v_add_f32_e32 v177, 1.0, v177
	v_add_f32_e32 v178, 1.0, v178
	v_add_f32_e32 v179, 1.0, v179
	v_rcp_f32_e32 v180, v164
	v_rcp_f32_e32 v181, v165
	v_rcp_f32_e32 v182, v166
	v_rcp_f32_e32 v183, v167
	v_rcp_f32_e32 v184, v168
	v_rcp_f32_e32 v185, v169
	v_rcp_f32_e32 v186, v170
	v_rcp_f32_e32 v187, v171
	v_rcp_f32_e32 v188, v172
	v_rcp_f32_e32 v189, v173
	v_rcp_f32_e32 v190, v174
	v_rcp_f32_e32 v191, v175
	v_rcp_f32_e32 v192, v176
	v_rcp_f32_e32 v193, v177
	v_rcp_f32_e32 v194, v178
	v_rcp_f32_e32 v195, v179
	s_cmp_eq_u32 s45, 0
	s_cbranch_scc1 .Lmy_eA_s31
	v_mul_f32_e32 v180, v38, v180
	v_mul_f32_e32 v181, v39, v181
	v_mul_f32_e32 v182, v40, v182
	v_mul_f32_e32 v183, v41, v183
	v_mul_f32_e32 v184, v34, v184
	v_mul_f32_e32 v185, v35, v185
	v_mul_f32_e32 v186, v36, v186
	v_mul_f32_e32 v187, v37, v187
	v_mul_f32_e32 v188, v10, v188
	v_mul_f32_e32 v189, v11, v189
	v_mul_f32_e32 v190, v12, v190
	v_mul_f32_e32 v191, v13, v191
	v_mul_f32_e32 v192, v2, v192
	v_mul_f32_e32 v193, v3, v193
	v_mul_f32_e32 v194, v4, v194
	v_mul_f32_e32 v195, v5, v195
.Lmy_eA_s31:
	v_cvt_pk_bf16_f32 v150, v180, v181
	v_cvt_pk_bf16_f32 v151, v182, v183
	v_cvt_pk_bf16_f32 v152, v184, v185
	v_cvt_pk_bf16_f32 v153, v186, v187
	global_store_dwordx4 v161, v[150:153], s[42:43] offset:128
	v_cvt_pk_bf16_f32 v154, v188, v189
	v_cvt_pk_bf16_f32 v155, v190, v191
	v_cvt_pk_bf16_f32 v156, v192, v193
	v_cvt_pk_bf16_f32 v157, v194, v195
	global_store_dwordx4 v161, v[154:157], s[42:43] offset:192
	s_mov_b64 s[8:9], exec
	s_branch .LBB0_249
.Lmy_eA_compiler:
	v_mov_b32_e32 v171, v210
	s_nop 0
	v_ashrrev_i32_e32 v169, 8, v171
	v_bfe_u32 v0, v171, 6, 2
	v_and_b32_e32 v131, 15, v171
	v_bfe_u32 v170, v171, 4, 2
	s_and_saveexec_b64 s[10:11], s[8:9]
	s_xor_b64 s[12:13], exec, s[10:11]
	s_cbranch_execz .LBB0_487
	v_cmp_lt_i32_e32 vcc, 8, v202
	s_mov_b64 s[10:11], 0
	v_cmp_eq_u32_e64 s[56:57], 9, v202
	s_and_saveexec_b64 s[8:9], vcc
	s_xor_b64 s[8:9], exec, s[8:9]
	s_and_b64 s[10:11], s[56:57], exec
	s_or_saveexec_b64 s[8:9], s[8:9]
	v_add_u32_e32 v130, -6, v202
	v_cmp_gt_u32_e64 s[58:59], 2, v130
	s_xor_b64 exec, exec, s[8:9]
	s_andn2_b64 s[10:11], s[10:11], exec
	s_and_b64 s[28:29], s[58:59], exec
	s_or_b64 s[10:11], s[10:11], s[28:29]
	s_or_b64 exec, exec, s[8:9]
	v_lshlrev_b32_e32 v130, 1, v131
	v_lshlrev_b32_e32 v0, 6, v0
	v_and_b32_e32 v130, 24, v130
	v_and_b32_e32 v131, 3, v171
	v_lshlrev_b64 v[164:165], 8, v[162:163]
	v_or3_b32 v205, v0, v130, v131
	v_or_b32_e32 v180, v164, v205
	v_mov_b32_e32 v181, v165
	v_lshlrev_b32_e32 v0, 5, v170
	v_lshl_add_u64 v[172:173], s[38:39], 0, v[0:1]
	v_lshl_add_u64 v[174:175], s[60:61], 0, v[0:1]
	v_lshlrev_b64 v[176:177], 7, v[180:181]
	s_and_saveexec_b64 s[8:9], s[10:11]
	s_cbranch_execz .LBB0_282
	v_lshl_add_u64 v[130:131], v[172:173], 0, v[176:177]
	v_lshl_add_u64 v[132:133], v[174:175], 0, v[176:177]
	global_load_dwordx4 v[146:149], v[130:131], off offset:16
	global_load_dwordx4 v[150:153], v[130:131], off
	global_load_dwordx4 v[154:157], v[132:133], off offset:16
	global_load_dwordx4 v[158:161], v[132:133], off
	v_or_b32_e32 v130, 0x200, v176
	v_mov_b32_e32 v131, v177
	v_lshl_add_u64 v[134:135], v[172:173], 0, v[130:131]
	v_lshl_add_u64 v[142:143], v[174:175], 0, v[130:131]
	global_load_dwordx4 v[130:133], v[134:135], off offset:16
	s_nop 0
	global_load_dwordx4 v[134:137], v[134:135], off
	s_nop 0
	global_load_dwordx4 v[138:141], v[142:143], off offset:16
	s_nop 0
	global_load_dwordx4 v[142:145], v[142:143], off
